# P14 final rmsnorm restructured: single load phase per row (16 rows/wave, loads issued 4 rows ahead, ssq partials via one 16B load + row_shr chain in baseline order, rstd in SGPR), on top of v_gdg
# baseline (speedup 1.0000x reference)
; __device__ __forceinline__ void phase_final(const Params& p) {
;     const int tid = threadIdx.x, lane = tid & 63, wave = tid >> 6, G = gridDim.x;
;     const int gw = blockIdx.x * NWAVES + wave, NGW = G * NWAVES;
;     const float* ssq = (const float*)(p.ws + WS_SSQ2); const f32x4* gr = (const f32x4*)p.in[I_NFG] + lane;
;     f32x4 g4[8];
; #pragma unroll
;     for (int j = 0; j < 8; ++j) g4[j] = gr[64 * j];
;     constexpr int UR = 4;
;     for (int row0 = gw; row0 < T; row0 += UR * NGW) { f32x4 v[UR][8]; float rs[UR];
; #pragma unroll
;         for (int u = 0; u < UR; ++u) { const int row = row0 + u * NGW; const f32x4* xr = (const f32x4*)(p.out + (size_t)row * DM) + lane;
; #pragma unroll
;             for (int j = 0; j < 8; ++j) v[u][j] = xr[64 * j];
;             const f32x4* sp = (const f32x4*)(ssq + (size_t)row * 32); f32x4 s = sp[0];
; #pragma unroll
;             for (int i = 1; i < 8; ++i) s += sp[i];
.LBB0_2001:
	s_cmp_lt_i32 s30, 15
	s_cselect_b64 s[4:5], -1, 0
	s_and_b64 s[0:1], s[4:5], s[0:1]
	s_andn2_b64 vcc, exec, s[0:1]
	s_cbranch_vccnz .LBB0_2005
	v_lshl_add_u32 v96, s96, 3, v145
	s_mov_b32 s0, 0x8000
	v_cmp_gt_i32_e32 vcc, s0, v96
	s_and_saveexec_b64 s[0:1], vcc
	s_cbranch_execz .LBB0_2005
	v_and_b32_e32 v240, 63, v144
	v_readfirstlane_b32 s4, v145
	v_lshlrev_b32_e32 v241, 4, v240
	v_and_b32_e32 v243, 7, v240
	v_add_u32_e32 v242, 0x1000, v241
	v_lshlrev_b32_e32 v243, 4, v243
	s_lshl_b32 s7, s96, 3
	s_add_u32 s7, s7, s4
	v_readlane_b32 s0, v244, 0
	s_waitcnt lgkmcnt(0)
	global_load_dwordx4 v[0:3], v241, s[24:25]
	global_load_dwordx4 v[4:7], v241, s[24:25] offset:1024
	global_load_dwordx4 v[8:11], v241, s[24:25] offset:2048
	global_load_dwordx4 v[12:15], v241, s[24:25] offset:3072
	global_load_dwordx4 v[16:19], v242, s[24:25]
	global_load_dwordx4 v[20:23], v242, s[24:25] offset:1024
	global_load_dwordx4 v[24:27], v242, s[24:25] offset:2048
	global_load_dwordx4 v[28:31], v242, s[24:25] offset:3072
	s_lshl_b32 s6, s0, 3
	s_add_u32 s2, s28, 0x8100000
	s_addc_u32 s3, s29, 0
	v_mov_b32_e32 v232, 0x358637bd
	v_mov_b32_e32 v233, 0x260
	s_mov_b32 s10, 0xf800000
	s_lshl_b32 s8, s7, 13
	s_add_u32 s36, s26, s8
	s_addc_u32 s37, s27, 0
	s_lshl_b32 s8, s7, 7
	s_add_u32 s60, s2, s8
	s_addc_u32 s61, s3, 0
	s_add_u32 s7, s7, s6
	global_load_dwordx4 v[160:163], v243, s[60:61]
	global_load_dwordx4 v[32:35], v241, s[36:37]
	global_load_dwordx4 v[36:39], v241, s[36:37] offset:1024
	global_load_dwordx4 v[40:43], v241, s[36:37] offset:2048
	global_load_dwordx4 v[44:47], v241, s[36:37] offset:3072
	global_load_dwordx4 v[48:51], v242, s[36:37]
	global_load_dwordx4 v[52:55], v242, s[36:37] offset:1024
	global_load_dwordx4 v[56:59], v242, s[36:37] offset:2048
	global_load_dwordx4 v[60:63], v242, s[36:37] offset:3072
	s_lshl_b32 s8, s7, 13
	s_add_u32 s38, s26, s8
	s_addc_u32 s39, s27, 0
	s_lshl_b32 s8, s7, 7
	s_add_u32 s62, s2, s8
	s_addc_u32 s63, s3, 0
	s_add_u32 s7, s7, s6
	global_load_dwordx4 v[164:167], v243, s[62:63]
	global_load_dwordx4 v[64:67], v241, s[38:39]
	global_load_dwordx4 v[68:71], v241, s[38:39] offset:1024
	global_load_dwordx4 v[72:75], v241, s[38:39] offset:2048
	global_load_dwordx4 v[76:79], v241, s[38:39] offset:3072
	global_load_dwordx4 v[80:83], v242, s[38:39]
	global_load_dwordx4 v[84:87], v242, s[38:39] offset:1024
	global_load_dwordx4 v[88:91], v242, s[38:39] offset:2048
	global_load_dwordx4 v[92:95], v242, s[38:39] offset:3072
	s_lshl_b32 s8, s7, 13
	s_add_u32 s40, s26, s8
	s_addc_u32 s41, s27, 0
	s_lshl_b32 s8, s7, 7
	s_add_u32 s64, s2, s8
	s_addc_u32 s65, s3, 0
	s_add_u32 s7, s7, s6
	global_load_dwordx4 v[168:171], v243, s[64:65]
	global_load_dwordx4 v[96:99], v241, s[40:41]
	global_load_dwordx4 v[100:103], v241, s[40:41] offset:1024
	global_load_dwordx4 v[104:107], v241, s[40:41] offset:2048
	global_load_dwordx4 v[108:111], v241, s[40:41] offset:3072
	global_load_dwordx4 v[112:115], v242, s[40:41]
	global_load_dwordx4 v[116:119], v242, s[40:41] offset:1024
	global_load_dwordx4 v[120:123], v242, s[40:41] offset:2048
	global_load_dwordx4 v[124:127], v242, s[40:41] offset:3072
	s_lshl_b32 s8, s7, 13
	s_add_u32 s42, s26, s8
	s_addc_u32 s43, s27, 0
	s_lshl_b32 s8, s7, 7
	s_add_u32 s66, s2, s8
	s_addc_u32 s67, s3, 0
	s_add_u32 s7, s7, s6
	global_load_dwordx4 v[172:175], v243, s[66:67]
	global_load_dwordx4 v[128:131], v241, s[42:43]
	global_load_dwordx4 v[132:135], v241, s[42:43] offset:1024
	global_load_dwordx4 v[136:139], v241, s[42:43] offset:2048
	global_load_dwordx4 v[140:143], v241, s[42:43] offset:3072
	global_load_dwordx4 v[144:147], v242, s[42:43]
	global_load_dwordx4 v[148:151], v242, s[42:43] offset:1024
	global_load_dwordx4 v[152:155], v242, s[42:43] offset:2048
	global_load_dwordx4 v[156:159], v242, s[42:43] offset:3072
	s_waitcnt vmcnt(35)
	v_mov_b32_e32 v176, v160
	v_mov_b32_e32 v177, v161
	v_mov_b32_e32 v178, v162
	v_mov_b32_e32 v179, v163
	v_add_f32_dpp v176, v176, v160 row_shr:1 row_mask:0xf bank_mask:0xf
	v_add_f32_dpp v177, v177, v161 row_shr:1 row_mask:0xf bank_mask:0xf
	v_add_f32_dpp v178, v178, v162 row_shr:1 row_mask:0xf bank_mask:0xf
	v_add_f32_dpp v179, v179, v163 row_shr:1 row_mask:0xf bank_mask:0xf
	v_add_f32_dpp v176, v176, v160 row_shr:1 row_mask:0xf bank_mask:0xf
	v_add_f32_dpp v177, v177, v161 row_shr:1 row_mask:0xf bank_mask:0xf
	v_add_f32_dpp v178, v178, v162 row_shr:1 row_mask:0xf bank_mask:0xf
	v_add_f32_dpp v179, v179, v163 row_shr:1 row_mask:0xf bank_mask:0xf
	v_add_f32_dpp v176, v176, v160 row_shr:1 row_mask:0xf bank_mask:0xf
	v_add_f32_dpp v177, v177, v161 row_shr:1 row_mask:0xf bank_mask:0xf
	v_add_f32_dpp v178, v178, v162 row_shr:1 row_mask:0xf bank_mask:0xf
	v_add_f32_dpp v179, v179, v163 row_shr:1 row_mask:0xf bank_mask:0xf
	v_add_f32_dpp v176, v176, v160 row_shr:1 row_mask:0xf bank_mask:0xf
	v_add_f32_dpp v177, v177, v161 row_shr:1 row_mask:0xf bank_mask:0xf
	v_add_f32_dpp v178, v178, v162 row_shr:1 row_mask:0xf bank_mask:0xf
	v_add_f32_dpp v179, v179, v163 row_shr:1 row_mask:0xf bank_mask:0xf
	v_add_f32_dpp v176, v176, v160 row_shr:1 row_mask:0xf bank_mask:0xf
	v_add_f32_dpp v177, v177, v161 row_shr:1 row_mask:0xf bank_mask:0xf
	v_add_f32_dpp v178, v178, v162 row_shr:1 row_mask:0xf bank_mask:0xf
	v_add_f32_dpp v179, v179, v163 row_shr:1 row_mask:0xf bank_mask:0xf
	v_add_f32_dpp v176, v176, v160 row_shr:1 row_mask:0xf bank_mask:0xf
	v_add_f32_dpp v177, v177, v161 row_shr:1 row_mask:0xf bank_mask:0xf
	v_add_f32_dpp v178, v178, v162 row_shr:1 row_mask:0xf bank_mask:0xf
	v_add_f32_dpp v179, v179, v163 row_shr:1 row_mask:0xf bank_mask:0xf
	v_add_f32_dpp v176, v176, v160 row_shr:1 row_mask:0xf bank_mask:0xf
; __device__ __forceinline__ void phase_final(const Params& p) {
;     ...
;         for (int u = 0; u < UR; ++u) { const int row = row0 + u * NGW; const f32x4* xr = (const f32x4*)(p.out + (size_t)row * DM) + lane;
; #pragma unroll
;             for (int j = 0; j < 8; ++j) v[u][j] = xr[64 * j];
;             const f32x4* sp = (const f32x4*)(ssq + (size_t)row * 32); f32x4 s = sp[0];
; #pragma unroll
;             for (int i = 1; i < 8; ++i) s += sp[i];
;             rs[u] = 1.0f / sqrtf(((s[0] + s[1]) + (s[2] + s[3])) * (1.0f / DM) + 1e-6f); }
; #pragma unroll
;         for (int u = 0; u < UR; ++u) { f32x4* xr = (f32x4*)(p.out + (size_t)(row0 + u * NGW) * DM) + lane;
; #pragma unroll
;             for (int j = 0; j < 8; ++j) __builtin_nontemporal_store(v[u][j] * rs[u] * g4[j], xr + 64 * j); } }
	v_add_f32_dpp v177, v177, v161 row_shr:1 row_mask:0xf bank_mask:0xf
	v_add_f32_dpp v178, v178, v162 row_shr:1 row_mask:0xf bank_mask:0xf
	v_add_f32_dpp v179, v179, v163 row_shr:1 row_mask:0xf bank_mask:0xf
	v_add_f32_e32 v227, v177, v176
	v_add_f32_e32 v229, v178, v179
	v_add_f32_e32 v212, v227, v229
	v_fmamk_f32 v213, v212, 0x3a000000, v232
	v_mul_f32_e32 v214, 0x4f800000, v213
	v_cmp_gt_f32_e32 vcc, s10, v213
	s_nop 1
	v_cndmask_b32_e32 v215, v213, v214, vcc
	v_sqrt_f32_e32 v216, v215
	s_nop 0
	v_add_u32_e32 v217, -1, v216
	v_add_u32_e32 v218, 1, v216
	v_fma_f32 v219, -v217, v216, v215
	v_fma_f32 v220, -v218, v216, v215
	v_cmp_ge_f32_e64 s[0:1], 0, v219
	s_nop 1
	v_cndmask_b32_e64 v221, v216, v217, s[0:1]
	v_cmp_lt_f32_e64 s[0:1], 0, v220
	s_nop 1
	v_cndmask_b32_e64 v221, v221, v218, s[0:1]
	v_mul_f32_e32 v222, 0x37800000, v221
	v_cndmask_b32_e32 v221, v221, v222, vcc
	v_cmp_class_f32_e32 vcc, v215, v233
	s_nop 1
	v_cndmask_b32_e32 v223, v221, v215, vcc
	v_div_scale_f32 v224, s[0:1], v223, v223, 1.0
	v_rcp_f32_e32 v225, v224
	v_div_scale_f32 v226, vcc, 1.0, v223, 1.0
	v_fma_f32 v227, -v224, v225, 1.0
	v_fmac_f32_e32 v225, v227, v225
	v_mul_f32_e32 v228, v226, v225
	v_fma_f32 v229, -v224, v228, v226
	v_fmac_f32_e32 v228, v229, v225
	v_fma_f32 v227, -v224, v228, v226
	v_div_fmas_f32 v230, v227, v225, v228
	v_div_fixup_f32 v231, v230, v223, 1.0
	s_nop 1
	v_readlane_b32 s52, v231, 7
	s_nop 1
	s_waitcnt vmcnt(34)
	v_pk_mul_f32 v[196:197], v[32:33], s[52:53] op_sel_hi:[1,0]
	v_pk_mul_f32 v[198:199], v[34:35], s[52:53] op_sel_hi:[1,0]
	v_pk_mul_f32 v[196:197], v[0:1], v[196:197]
	v_pk_mul_f32 v[198:199], v[2:3], v[198:199]
	global_store_dwordx4 v241, v[196:199], s[36:37] nt
	s_waitcnt vmcnt(34)
	v_pk_mul_f32 v[200:201], v[36:37], s[52:53] op_sel_hi:[1,0]
	v_pk_mul_f32 v[202:203], v[38:39], s[52:53] op_sel_hi:[1,0]
	v_pk_mul_f32 v[200:201], v[4:5], v[200:201]
	v_pk_mul_f32 v[202:203], v[6:7], v[202:203]
	global_store_dwordx4 v241, v[200:203], s[36:37] offset:1024 nt
	s_waitcnt vmcnt(34)
	v_pk_mul_f32 v[204:205], v[40:41], s[52:53] op_sel_hi:[1,0]
	v_pk_mul_f32 v[206:207], v[42:43], s[52:53] op_sel_hi:[1,0]
	v_pk_mul_f32 v[204:205], v[8:9], v[204:205]
	v_pk_mul_f32 v[206:207], v[10:11], v[206:207]
	global_store_dwordx4 v241, v[204:207], s[36:37] offset:2048 nt
	s_waitcnt vmcnt(34)
	v_pk_mul_f32 v[208:209], v[44:45], s[52:53] op_sel_hi:[1,0]
	v_pk_mul_f32 v[210:211], v[46:47], s[52:53] op_sel_hi:[1,0]
	v_pk_mul_f32 v[208:209], v[12:13], v[208:209]
	v_pk_mul_f32 v[210:211], v[14:15], v[210:211]
	global_store_dwordx4 v241, v[208:211], s[36:37] offset:3072 nt
	s_waitcnt vmcnt(34)
	v_pk_mul_f32 v[196:197], v[48:49], s[52:53] op_sel_hi:[1,0]
	v_pk_mul_f32 v[198:199], v[50:51], s[52:53] op_sel_hi:[1,0]
	v_pk_mul_f32 v[196:197], v[16:17], v[196:197]
	v_pk_mul_f32 v[198:199], v[18:19], v[198:199]
	global_store_dwordx4 v242, v[196:199], s[36:37] nt
	s_waitcnt vmcnt(34)
	v_pk_mul_f32 v[200:201], v[52:53], s[52:53] op_sel_hi:[1,0]
	v_pk_mul_f32 v[202:203], v[54:55], s[52:53] op_sel_hi:[1,0]
	v_pk_mul_f32 v[200:201], v[20:21], v[200:201]
	v_pk_mul_f32 v[202:203], v[22:23], v[202:203]
	global_store_dwordx4 v242, v[200:203], s[36:37] offset:1024 nt
	s_waitcnt vmcnt(34)
	v_pk_mul_f32 v[204:205], v[56:57], s[52:53] op_sel_hi:[1,0]
	v_pk_mul_f32 v[206:207], v[58:59], s[52:53] op_sel_hi:[1,0]
	v_pk_mul_f32 v[204:205], v[24:25], v[204:205]
	v_pk_mul_f32 v[206:207], v[26:27], v[206:207]
	global_store_dwordx4 v242, v[204:207], s[36:37] offset:2048 nt
	s_waitcnt vmcnt(34)
	v_pk_mul_f32 v[208:209], v[60:61], s[52:53] op_sel_hi:[1,0]
	v_pk_mul_f32 v[210:211], v[62:63], s[52:53] op_sel_hi:[1,0]
	v_pk_mul_f32 v[208:209], v[28:29], v[208:209]
	v_pk_mul_f32 v[210:211], v[30:31], v[210:211]
	global_store_dwordx4 v242, v[208:211], s[36:37] offset:3072 nt
	s_lshl_b32 s8, s7, 13
	s_add_u32 s44, s26, s8
	s_addc_u32 s45, s27, 0
	s_lshl_b32 s8, s7, 7
	s_add_u32 s68, s2, s8
	s_addc_u32 s69, s3, 0
	s_add_u32 s7, s7, s6
	global_load_dwordx4 v[160:163], v243, s[68:69]
	global_load_dwordx4 v[32:35], v241, s[44:45]
	global_load_dwordx4 v[36:39], v241, s[44:45] offset:1024
	global_load_dwordx4 v[40:43], v241, s[44:45] offset:2048
	global_load_dwordx4 v[44:47], v241, s[44:45] offset:3072
	global_load_dwordx4 v[48:51], v242, s[44:45]
	global_load_dwordx4 v[52:55], v242, s[44:45] offset:1024
	global_load_dwordx4 v[56:59], v242, s[44:45] offset:2048
	global_load_dwordx4 v[60:63], v242, s[44:45] offset:3072
	s_waitcnt vmcnt(43)
; __device__ __forceinline__ void phase_final(const Params& p) {
;     ...
;             const f32x4* sp = (const f32x4*)(ssq + (size_t)row * 32); f32x4 s = sp[0];
; #pragma unroll
;             for (int i = 1; i < 8; ++i) s += sp[i];
;             rs[u] = 1.0f / sqrtf(((s[0] + s[1]) + (s[2] + s[3])) * (1.0f / DM) + 1e-6f); }
; #pragma unroll
;         for (int u = 0; u < UR; ++u) { f32x4* xr = (f32x4*)(p.out + (size_t)(row0 + u * NGW) * DM) + lane;
; #pragma unroll
;             for (int j = 0; j < 8; ++j) __builtin_nontemporal_store(v[u][j] * rs[u] * g4[j], xr + 64 * j); } }
	v_mov_b32_e32 v180, v164
	v_mov_b32_e32 v181, v165
	v_mov_b32_e32 v182, v166
	v_mov_b32_e32 v183, v167
	v_add_f32_dpp v180, v180, v164 row_shr:1 row_mask:0xf bank_mask:0xf
	v_add_f32_dpp v181, v181, v165 row_shr:1 row_mask:0xf bank_mask:0xf
	v_add_f32_dpp v182, v182, v166 row_shr:1 row_mask:0xf bank_mask:0xf
	v_add_f32_dpp v183, v183, v167 row_shr:1 row_mask:0xf bank_mask:0xf
	v_add_f32_dpp v180, v180, v164 row_shr:1 row_mask:0xf bank_mask:0xf
	v_add_f32_dpp v181, v181, v165 row_shr:1 row_mask:0xf bank_mask:0xf
	v_add_f32_dpp v182, v182, v166 row_shr:1 row_mask:0xf bank_mask:0xf
	v_add_f32_dpp v183, v183, v167 row_shr:1 row_mask:0xf bank_mask:0xf
	v_add_f32_dpp v180, v180, v164 row_shr:1 row_mask:0xf bank_mask:0xf
	v_add_f32_dpp v181, v181, v165 row_shr:1 row_mask:0xf bank_mask:0xf
	v_add_f32_dpp v182, v182, v166 row_shr:1 row_mask:0xf bank_mask:0xf
	v_add_f32_dpp v183, v183, v167 row_shr:1 row_mask:0xf bank_mask:0xf
	v_add_f32_dpp v180, v180, v164 row_shr:1 row_mask:0xf bank_mask:0xf
	v_add_f32_dpp v181, v181, v165 row_shr:1 row_mask:0xf bank_mask:0xf
	v_add_f32_dpp v182, v182, v166 row_shr:1 row_mask:0xf bank_mask:0xf
	v_add_f32_dpp v183, v183, v167 row_shr:1 row_mask:0xf bank_mask:0xf
	v_add_f32_dpp v180, v180, v164 row_shr:1 row_mask:0xf bank_mask:0xf
	v_add_f32_dpp v181, v181, v165 row_shr:1 row_mask:0xf bank_mask:0xf
	v_add_f32_dpp v182, v182, v166 row_shr:1 row_mask:0xf bank_mask:0xf
	v_add_f32_dpp v183, v183, v167 row_shr:1 row_mask:0xf bank_mask:0xf
	v_add_f32_dpp v180, v180, v164 row_shr:1 row_mask:0xf bank_mask:0xf
	v_add_f32_dpp v181, v181, v165 row_shr:1 row_mask:0xf bank_mask:0xf
	v_add_f32_dpp v182, v182, v166 row_shr:1 row_mask:0xf bank_mask:0xf
	v_add_f32_dpp v183, v183, v167 row_shr:1 row_mask:0xf bank_mask:0xf
	v_add_f32_dpp v180, v180, v164 row_shr:1 row_mask:0xf bank_mask:0xf
	v_add_f32_dpp v181, v181, v165 row_shr:1 row_mask:0xf bank_mask:0xf
	v_add_f32_dpp v182, v182, v166 row_shr:1 row_mask:0xf bank_mask:0xf
	v_add_f32_dpp v183, v183, v167 row_shr:1 row_mask:0xf bank_mask:0xf
	v_add_f32_e32 v227, v181, v180
	v_add_f32_e32 v229, v182, v183
	v_add_f32_e32 v212, v227, v229
	v_fmamk_f32 v213, v212, 0x3a000000, v232
	v_mul_f32_e32 v214, 0x4f800000, v213
	v_cmp_gt_f32_e32 vcc, s10, v213
	s_nop 1
	v_cndmask_b32_e32 v215, v213, v214, vcc
	v_sqrt_f32_e32 v216, v215
	s_nop 0
	v_add_u32_e32 v217, -1, v216
	v_add_u32_e32 v218, 1, v216
	v_fma_f32 v219, -v217, v216, v215
	v_fma_f32 v220, -v218, v216, v215
	v_cmp_ge_f32_e64 s[0:1], 0, v219
	s_nop 1
	v_cndmask_b32_e64 v221, v216, v217, s[0:1]
	v_cmp_lt_f32_e64 s[0:1], 0, v220
	s_nop 1
	v_cndmask_b32_e64 v221, v221, v218, s[0:1]
	v_mul_f32_e32 v222, 0x37800000, v221
	v_cndmask_b32_e32 v221, v221, v222, vcc
	v_cmp_class_f32_e32 vcc, v215, v233
	s_nop 1
	v_cndmask_b32_e32 v223, v221, v215, vcc
	v_div_scale_f32 v224, s[0:1], v223, v223, 1.0
	v_rcp_f32_e32 v225, v224
	v_div_scale_f32 v226, vcc, 1.0, v223, 1.0
	v_fma_f32 v227, -v224, v225, 1.0
	v_fmac_f32_e32 v225, v227, v225
	v_mul_f32_e32 v228, v226, v225
	v_fma_f32 v229, -v224, v228, v226
	v_fmac_f32_e32 v228, v229, v225
	v_fma_f32 v227, -v224, v228, v226
	v_div_fmas_f32 v230, v227, v225, v228
	v_div_fixup_f32 v231, v230, v223, 1.0
	s_nop 1
	v_readlane_b32 s54, v231, 7
	s_nop 1
	s_waitcnt vmcnt(42)
	v_pk_mul_f32 v[196:197], v[64:65], s[54:55] op_sel_hi:[1,0]
	v_pk_mul_f32 v[198:199], v[66:67], s[54:55] op_sel_hi:[1,0]
	v_pk_mul_f32 v[196:197], v[0:1], v[196:197]
	v_pk_mul_f32 v[198:199], v[2:3], v[198:199]
	global_store_dwordx4 v241, v[196:199], s[38:39] nt
	s_waitcnt vmcnt(42)
	v_pk_mul_f32 v[200:201], v[68:69], s[54:55] op_sel_hi:[1,0]
	v_pk_mul_f32 v[202:203], v[70:71], s[54:55] op_sel_hi:[1,0]
	v_pk_mul_f32 v[200:201], v[4:5], v[200:201]
	v_pk_mul_f32 v[202:203], v[6:7], v[202:203]
	global_store_dwordx4 v241, v[200:203], s[38:39] offset:1024 nt
	s_waitcnt vmcnt(42)
	v_pk_mul_f32 v[204:205], v[72:73], s[54:55] op_sel_hi:[1,0]
	v_pk_mul_f32 v[206:207], v[74:75], s[54:55] op_sel_hi:[1,0]
	v_pk_mul_f32 v[204:205], v[8:9], v[204:205]
	v_pk_mul_f32 v[206:207], v[10:11], v[206:207]
	global_store_dwordx4 v241, v[204:207], s[38:39] offset:2048 nt
	s_waitcnt vmcnt(42)
	v_pk_mul_f32 v[208:209], v[76:77], s[54:55] op_sel_hi:[1,0]
	v_pk_mul_f32 v[210:211], v[78:79], s[54:55] op_sel_hi:[1,0]
	v_pk_mul_f32 v[208:209], v[12:13], v[208:209]
	v_pk_mul_f32 v[210:211], v[14:15], v[210:211]
	global_store_dwordx4 v241, v[208:211], s[38:39] offset:3072 nt
	s_waitcnt vmcnt(42)
	v_pk_mul_f32 v[196:197], v[80:81], s[54:55] op_sel_hi:[1,0]
	v_pk_mul_f32 v[198:199], v[82:83], s[54:55] op_sel_hi:[1,0]
	v_pk_mul_f32 v[196:197], v[16:17], v[196:197]
	v_pk_mul_f32 v[198:199], v[18:19], v[198:199]
	global_store_dwordx4 v242, v[196:199], s[38:39] nt
	s_waitcnt vmcnt(42)
	v_pk_mul_f32 v[200:201], v[84:85], s[54:55] op_sel_hi:[1,0]
	v_pk_mul_f32 v[202:203], v[86:87], s[54:55] op_sel_hi:[1,0]
	v_pk_mul_f32 v[200:201], v[20:21], v[200:201]
	v_pk_mul_f32 v[202:203], v[22:23], v[202:203]
	global_store_dwordx4 v242, v[200:203], s[38:39] offset:1024 nt
	s_waitcnt vmcnt(42)
	v_pk_mul_f32 v[204:205], v[88:89], s[54:55] op_sel_hi:[1,0]
	v_pk_mul_f32 v[206:207], v[90:91], s[54:55] op_sel_hi:[1,0]
	v_pk_mul_f32 v[204:205], v[24:25], v[204:205]
	v_pk_mul_f32 v[206:207], v[26:27], v[206:207]
	global_store_dwordx4 v242, v[204:207], s[38:39] offset:2048 nt
	s_waitcnt vmcnt(42)
; __device__ __forceinline__ void phase_final(const Params& p) {
;     ...
;         for (int u = 0; u < UR; ++u) { const int row = row0 + u * NGW; const f32x4* xr = (const f32x4*)(p.out + (size_t)row * DM) + lane;
; #pragma unroll
;             for (int j = 0; j < 8; ++j) v[u][j] = xr[64 * j];
;             const f32x4* sp = (const f32x4*)(ssq + (size_t)row * 32); f32x4 s = sp[0];
; #pragma unroll
;             for (int i = 1; i < 8; ++i) s += sp[i];
;             rs[u] = 1.0f / sqrtf(((s[0] + s[1]) + (s[2] + s[3])) * (1.0f / DM) + 1e-6f); }
; #pragma unroll
;         for (int u = 0; u < UR; ++u) { f32x4* xr = (f32x4*)(p.out + (size_t)(row0 + u * NGW) * DM) + lane;
; #pragma unroll
;             for (int j = 0; j < 8; ++j) __builtin_nontemporal_store(v[u][j] * rs[u] * g4[j], xr + 64 * j); } }
	v_pk_mul_f32 v[208:209], v[92:93], s[54:55] op_sel_hi:[1,0]
	v_pk_mul_f32 v[210:211], v[94:95], s[54:55] op_sel_hi:[1,0]
	v_pk_mul_f32 v[208:209], v[28:29], v[208:209]
	v_pk_mul_f32 v[210:211], v[30:31], v[210:211]
	global_store_dwordx4 v242, v[208:211], s[38:39] offset:3072 nt
	s_lshl_b32 s8, s7, 13
	s_add_u32 s46, s26, s8
	s_addc_u32 s47, s27, 0
	s_lshl_b32 s8, s7, 7
	s_add_u32 s70, s2, s8
	s_addc_u32 s71, s3, 0
	s_add_u32 s7, s7, s6
	global_load_dwordx4 v[164:167], v243, s[70:71]
	global_load_dwordx4 v[64:67], v241, s[46:47]
	global_load_dwordx4 v[68:71], v241, s[46:47] offset:1024
	global_load_dwordx4 v[72:75], v241, s[46:47] offset:2048
	global_load_dwordx4 v[76:79], v241, s[46:47] offset:3072
	global_load_dwordx4 v[80:83], v242, s[46:47]
	global_load_dwordx4 v[84:87], v242, s[46:47] offset:1024
	global_load_dwordx4 v[88:91], v242, s[46:47] offset:2048
	global_load_dwordx4 v[92:95], v242, s[46:47] offset:3072
	s_waitcnt vmcnt(51)
	v_mov_b32_e32 v184, v168
	v_mov_b32_e32 v185, v169
	v_mov_b32_e32 v186, v170
	v_mov_b32_e32 v187, v171
	v_add_f32_dpp v184, v184, v168 row_shr:1 row_mask:0xf bank_mask:0xf
	v_add_f32_dpp v185, v185, v169 row_shr:1 row_mask:0xf bank_mask:0xf
	v_add_f32_dpp v186, v186, v170 row_shr:1 row_mask:0xf bank_mask:0xf
	v_add_f32_dpp v187, v187, v171 row_shr:1 row_mask:0xf bank_mask:0xf
	v_add_f32_dpp v184, v184, v168 row_shr:1 row_mask:0xf bank_mask:0xf
	v_add_f32_dpp v185, v185, v169 row_shr:1 row_mask:0xf bank_mask:0xf
	v_add_f32_dpp v186, v186, v170 row_shr:1 row_mask:0xf bank_mask:0xf
	v_add_f32_dpp v187, v187, v171 row_shr:1 row_mask:0xf bank_mask:0xf
	v_add_f32_dpp v184, v184, v168 row_shr:1 row_mask:0xf bank_mask:0xf
	v_add_f32_dpp v185, v185, v169 row_shr:1 row_mask:0xf bank_mask:0xf
	v_add_f32_dpp v186, v186, v170 row_shr:1 row_mask:0xf bank_mask:0xf
	v_add_f32_dpp v187, v187, v171 row_shr:1 row_mask:0xf bank_mask:0xf
	v_add_f32_dpp v184, v184, v168 row_shr:1 row_mask:0xf bank_mask:0xf
	v_add_f32_dpp v185, v185, v169 row_shr:1 row_mask:0xf bank_mask:0xf
	v_add_f32_dpp v186, v186, v170 row_shr:1 row_mask:0xf bank_mask:0xf
	v_add_f32_dpp v187, v187, v171 row_shr:1 row_mask:0xf bank_mask:0xf
	v_add_f32_dpp v184, v184, v168 row_shr:1 row_mask:0xf bank_mask:0xf
	v_add_f32_dpp v185, v185, v169 row_shr:1 row_mask:0xf bank_mask:0xf
	v_add_f32_dpp v186, v186, v170 row_shr:1 row_mask:0xf bank_mask:0xf
	v_add_f32_dpp v187, v187, v171 row_shr:1 row_mask:0xf bank_mask:0xf
	v_add_f32_dpp v184, v184, v168 row_shr:1 row_mask:0xf bank_mask:0xf
	v_add_f32_dpp v185, v185, v169 row_shr:1 row_mask:0xf bank_mask:0xf
	v_add_f32_dpp v186, v186, v170 row_shr:1 row_mask:0xf bank_mask:0xf
	v_add_f32_dpp v187, v187, v171 row_shr:1 row_mask:0xf bank_mask:0xf
	v_add_f32_dpp v184, v184, v168 row_shr:1 row_mask:0xf bank_mask:0xf
	v_add_f32_dpp v185, v185, v169 row_shr:1 row_mask:0xf bank_mask:0xf
	v_add_f32_dpp v186, v186, v170 row_shr:1 row_mask:0xf bank_mask:0xf
	v_add_f32_dpp v187, v187, v171 row_shr:1 row_mask:0xf bank_mask:0xf
	v_add_f32_e32 v227, v185, v184
	v_add_f32_e32 v229, v186, v187
	v_add_f32_e32 v212, v227, v229
	v_fmamk_f32 v213, v212, 0x3a000000, v232
	v_mul_f32_e32 v214, 0x4f800000, v213
	v_cmp_gt_f32_e32 vcc, s10, v213
	s_nop 1
	v_cndmask_b32_e32 v215, v213, v214, vcc
	v_sqrt_f32_e32 v216, v215
	s_nop 0
	v_add_u32_e32 v217, -1, v216
	v_add_u32_e32 v218, 1, v216
	v_fma_f32 v219, -v217, v216, v215
	v_fma_f32 v220, -v218, v216, v215
	v_cmp_ge_f32_e64 s[0:1], 0, v219
	s_nop 1
	v_cndmask_b32_e64 v221, v216, v217, s[0:1]
	v_cmp_lt_f32_e64 s[0:1], 0, v220
	s_nop 1
	v_cndmask_b32_e64 v221, v221, v218, s[0:1]
	v_mul_f32_e32 v222, 0x37800000, v221
	v_cndmask_b32_e32 v221, v221, v222, vcc
	v_cmp_class_f32_e32 vcc, v215, v233
	s_nop 1
	v_cndmask_b32_e32 v223, v221, v215, vcc
	v_div_scale_f32 v224, s[0:1], v223, v223, 1.0
	v_rcp_f32_e32 v225, v224
	v_div_scale_f32 v226, vcc, 1.0, v223, 1.0
	v_fma_f32 v227, -v224, v225, 1.0
	v_fmac_f32_e32 v225, v227, v225
	v_mul_f32_e32 v228, v226, v225
	v_fma_f32 v229, -v224, v228, v226
	v_fmac_f32_e32 v228, v229, v225
	v_fma_f32 v227, -v224, v228, v226
	v_div_fmas_f32 v230, v227, v225, v228
	v_div_fixup_f32 v231, v230, v223, 1.0
	s_nop 1
	v_readlane_b32 s56, v231, 7
	s_nop 1
	s_waitcnt vmcnt(50)
	v_pk_mul_f32 v[196:197], v[96:97], s[56:57] op_sel_hi:[1,0]
	v_pk_mul_f32 v[198:199], v[98:99], s[56:57] op_sel_hi:[1,0]
	v_pk_mul_f32 v[196:197], v[0:1], v[196:197]
	v_pk_mul_f32 v[198:199], v[2:3], v[198:199]
	global_store_dwordx4 v241, v[196:199], s[40:41] nt
	s_waitcnt vmcnt(50)
	v_pk_mul_f32 v[200:201], v[100:101], s[56:57] op_sel_hi:[1,0]
	v_pk_mul_f32 v[202:203], v[102:103], s[56:57] op_sel_hi:[1,0]
	v_pk_mul_f32 v[200:201], v[4:5], v[200:201]
	v_pk_mul_f32 v[202:203], v[6:7], v[202:203]
	global_store_dwordx4 v241, v[200:203], s[40:41] offset:1024 nt
	s_waitcnt vmcnt(50)
	v_pk_mul_f32 v[204:205], v[104:105], s[56:57] op_sel_hi:[1,0]
	v_pk_mul_f32 v[206:207], v[106:107], s[56:57] op_sel_hi:[1,0]
	v_pk_mul_f32 v[204:205], v[8:9], v[204:205]
	v_pk_mul_f32 v[206:207], v[10:11], v[206:207]
	global_store_dwordx4 v241, v[204:207], s[40:41] offset:2048 nt
	s_waitcnt vmcnt(50)
	v_pk_mul_f32 v[208:209], v[108:109], s[56:57] op_sel_hi:[1,0]
	v_pk_mul_f32 v[210:211], v[110:111], s[56:57] op_sel_hi:[1,0]
	v_pk_mul_f32 v[208:209], v[12:13], v[208:209]
	v_pk_mul_f32 v[210:211], v[14:15], v[210:211]
	global_store_dwordx4 v241, v[208:211], s[40:41] offset:3072 nt
	s_waitcnt vmcnt(50)
	v_pk_mul_f32 v[196:197], v[112:113], s[56:57] op_sel_hi:[1,0]
	v_pk_mul_f32 v[198:199], v[114:115], s[56:57] op_sel_hi:[1,0]
	v_pk_mul_f32 v[196:197], v[16:17], v[196:197]
	v_pk_mul_f32 v[198:199], v[18:19], v[198:199]
	global_store_dwordx4 v242, v[196:199], s[40:41] nt
	s_waitcnt vmcnt(50)
; __device__ __forceinline__ void phase_final(const Params& p) {
;     ...
;         for (int u = 0; u < UR; ++u) { const int row = row0 + u * NGW; const f32x4* xr = (const f32x4*)(p.out + (size_t)row * DM) + lane;
; #pragma unroll
;             for (int j = 0; j < 8; ++j) v[u][j] = xr[64 * j];
;             const f32x4* sp = (const f32x4*)(ssq + (size_t)row * 32); f32x4 s = sp[0];
; #pragma unroll
;             for (int i = 1; i < 8; ++i) s += sp[i];
;             rs[u] = 1.0f / sqrtf(((s[0] + s[1]) + (s[2] + s[3])) * (1.0f / DM) + 1e-6f); }
; #pragma unroll
;         for (int u = 0; u < UR; ++u) { f32x4* xr = (f32x4*)(p.out + (size_t)(row0 + u * NGW) * DM) + lane;
; #pragma unroll
;             for (int j = 0; j < 8; ++j) __builtin_nontemporal_store(v[u][j] * rs[u] * g4[j], xr + 64 * j); } }
	v_pk_mul_f32 v[200:201], v[116:117], s[56:57] op_sel_hi:[1,0]
	v_pk_mul_f32 v[202:203], v[118:119], s[56:57] op_sel_hi:[1,0]
	v_pk_mul_f32 v[200:201], v[20:21], v[200:201]
	v_pk_mul_f32 v[202:203], v[22:23], v[202:203]
	global_store_dwordx4 v242, v[200:203], s[40:41] offset:1024 nt
	s_waitcnt vmcnt(50)
	v_pk_mul_f32 v[204:205], v[120:121], s[56:57] op_sel_hi:[1,0]
	v_pk_mul_f32 v[206:207], v[122:123], s[56:57] op_sel_hi:[1,0]
	v_pk_mul_f32 v[204:205], v[24:25], v[204:205]
	v_pk_mul_f32 v[206:207], v[26:27], v[206:207]
	global_store_dwordx4 v242, v[204:207], s[40:41] offset:2048 nt
	s_waitcnt vmcnt(50)
	v_pk_mul_f32 v[208:209], v[124:125], s[56:57] op_sel_hi:[1,0]
	v_pk_mul_f32 v[210:211], v[126:127], s[56:57] op_sel_hi:[1,0]
	v_pk_mul_f32 v[208:209], v[28:29], v[208:209]
	v_pk_mul_f32 v[210:211], v[30:31], v[210:211]
	global_store_dwordx4 v242, v[208:211], s[40:41] offset:3072 nt
	s_lshl_b32 s8, s7, 13
	s_add_u32 s48, s26, s8
	s_addc_u32 s49, s27, 0
	s_lshl_b32 s8, s7, 7
	s_add_u32 s72, s2, s8
	s_addc_u32 s73, s3, 0
	s_add_u32 s7, s7, s6
	global_load_dwordx4 v[168:171], v243, s[72:73]
	global_load_dwordx4 v[96:99], v241, s[48:49]
	global_load_dwordx4 v[100:103], v241, s[48:49] offset:1024
	global_load_dwordx4 v[104:107], v241, s[48:49] offset:2048
	global_load_dwordx4 v[108:111], v241, s[48:49] offset:3072
	global_load_dwordx4 v[112:115], v242, s[48:49]
	global_load_dwordx4 v[116:119], v242, s[48:49] offset:1024
	global_load_dwordx4 v[120:123], v242, s[48:49] offset:2048
	global_load_dwordx4 v[124:127], v242, s[48:49] offset:3072
	s_waitcnt vmcnt(59)
	v_mov_b32_e32 v188, v172
	v_mov_b32_e32 v189, v173
	v_mov_b32_e32 v190, v174
	v_mov_b32_e32 v191, v175
	v_add_f32_dpp v188, v188, v172 row_shr:1 row_mask:0xf bank_mask:0xf
	v_add_f32_dpp v189, v189, v173 row_shr:1 row_mask:0xf bank_mask:0xf
	v_add_f32_dpp v190, v190, v174 row_shr:1 row_mask:0xf bank_mask:0xf
	v_add_f32_dpp v191, v191, v175 row_shr:1 row_mask:0xf bank_mask:0xf
	v_add_f32_dpp v188, v188, v172 row_shr:1 row_mask:0xf bank_mask:0xf
	v_add_f32_dpp v189, v189, v173 row_shr:1 row_mask:0xf bank_mask:0xf
	v_add_f32_dpp v190, v190, v174 row_shr:1 row_mask:0xf bank_mask:0xf
	v_add_f32_dpp v191, v191, v175 row_shr:1 row_mask:0xf bank_mask:0xf
	v_add_f32_dpp v188, v188, v172 row_shr:1 row_mask:0xf bank_mask:0xf
	v_add_f32_dpp v189, v189, v173 row_shr:1 row_mask:0xf bank_mask:0xf
	v_add_f32_dpp v190, v190, v174 row_shr:1 row_mask:0xf bank_mask:0xf
	v_add_f32_dpp v191, v191, v175 row_shr:1 row_mask:0xf bank_mask:0xf
	v_add_f32_dpp v188, v188, v172 row_shr:1 row_mask:0xf bank_mask:0xf
	v_add_f32_dpp v189, v189, v173 row_shr:1 row_mask:0xf bank_mask:0xf
	v_add_f32_dpp v190, v190, v174 row_shr:1 row_mask:0xf bank_mask:0xf
	v_add_f32_dpp v191, v191, v175 row_shr:1 row_mask:0xf bank_mask:0xf
	v_add_f32_dpp v188, v188, v172 row_shr:1 row_mask:0xf bank_mask:0xf
	v_add_f32_dpp v189, v189, v173 row_shr:1 row_mask:0xf bank_mask:0xf
	v_add_f32_dpp v190, v190, v174 row_shr:1 row_mask:0xf bank_mask:0xf
	v_add_f32_dpp v191, v191, v175 row_shr:1 row_mask:0xf bank_mask:0xf
	v_add_f32_dpp v188, v188, v172 row_shr:1 row_mask:0xf bank_mask:0xf
	v_add_f32_dpp v189, v189, v173 row_shr:1 row_mask:0xf bank_mask:0xf
	v_add_f32_dpp v190, v190, v174 row_shr:1 row_mask:0xf bank_mask:0xf
	v_add_f32_dpp v191, v191, v175 row_shr:1 row_mask:0xf bank_mask:0xf
	v_add_f32_dpp v188, v188, v172 row_shr:1 row_mask:0xf bank_mask:0xf
	v_add_f32_dpp v189, v189, v173 row_shr:1 row_mask:0xf bank_mask:0xf
	v_add_f32_dpp v190, v190, v174 row_shr:1 row_mask:0xf bank_mask:0xf
	v_add_f32_dpp v191, v191, v175 row_shr:1 row_mask:0xf bank_mask:0xf
	v_add_f32_e32 v227, v189, v188
	v_add_f32_e32 v229, v190, v191
	v_add_f32_e32 v212, v227, v229
	v_fmamk_f32 v213, v212, 0x3a000000, v232
	v_mul_f32_e32 v214, 0x4f800000, v213
	v_cmp_gt_f32_e32 vcc, s10, v213
	s_nop 1
	v_cndmask_b32_e32 v215, v213, v214, vcc
	v_sqrt_f32_e32 v216, v215
	s_nop 0
	v_add_u32_e32 v217, -1, v216
	v_add_u32_e32 v218, 1, v216
	v_fma_f32 v219, -v217, v216, v215
	v_fma_f32 v220, -v218, v216, v215
	v_cmp_ge_f32_e64 s[0:1], 0, v219
	s_nop 1
	v_cndmask_b32_e64 v221, v216, v217, s[0:1]
	v_cmp_lt_f32_e64 s[0:1], 0, v220
	s_nop 1
	v_cndmask_b32_e64 v221, v221, v218, s[0:1]
	v_mul_f32_e32 v222, 0x37800000, v221
	v_cndmask_b32_e32 v221, v221, v222, vcc
	v_cmp_class_f32_e32 vcc, v215, v233
	s_nop 1
	v_cndmask_b32_e32 v223, v221, v215, vcc
	v_div_scale_f32 v224, s[0:1], v223, v223, 1.0
	v_rcp_f32_e32 v225, v224
	v_div_scale_f32 v226, vcc, 1.0, v223, 1.0
	v_fma_f32 v227, -v224, v225, 1.0
	v_fmac_f32_e32 v225, v227, v225
	v_mul_f32_e32 v228, v226, v225
	v_fma_f32 v229, -v224, v228, v226
	v_fmac_f32_e32 v228, v229, v225
	v_fma_f32 v227, -v224, v228, v226
	v_div_fmas_f32 v230, v227, v225, v228
	v_div_fixup_f32 v231, v230, v223, 1.0
	s_nop 1
	v_readlane_b32 s58, v231, 7
	s_nop 1
	s_waitcnt vmcnt(58)
	v_pk_mul_f32 v[196:197], v[128:129], s[58:59] op_sel_hi:[1,0]
	v_pk_mul_f32 v[198:199], v[130:131], s[58:59] op_sel_hi:[1,0]
	v_pk_mul_f32 v[196:197], v[0:1], v[196:197]
	v_pk_mul_f32 v[198:199], v[2:3], v[198:199]
	global_store_dwordx4 v241, v[196:199], s[42:43] nt
	s_waitcnt vmcnt(58)
	v_pk_mul_f32 v[200:201], v[132:133], s[58:59] op_sel_hi:[1,0]
	v_pk_mul_f32 v[202:203], v[134:135], s[58:59] op_sel_hi:[1,0]
	v_pk_mul_f32 v[200:201], v[4:5], v[200:201]
	v_pk_mul_f32 v[202:203], v[6:7], v[202:203]
	global_store_dwordx4 v241, v[200:203], s[42:43] offset:1024 nt
	s_waitcnt vmcnt(58)
	v_pk_mul_f32 v[204:205], v[136:137], s[58:59] op_sel_hi:[1,0]
	v_pk_mul_f32 v[206:207], v[138:139], s[58:59] op_sel_hi:[1,0]
	v_pk_mul_f32 v[204:205], v[8:9], v[204:205]
	v_pk_mul_f32 v[206:207], v[10:11], v[206:207]
	global_store_dwordx4 v241, v[204:207], s[42:43] offset:2048 nt
	s_waitcnt vmcnt(58)
; __device__ __forceinline__ void phase_final(const Params& p) {
;     ...
;         for (int u = 0; u < UR; ++u) { const int row = row0 + u * NGW; const f32x4* xr = (const f32x4*)(p.out + (size_t)row * DM) + lane;
; #pragma unroll
;             for (int j = 0; j < 8; ++j) v[u][j] = xr[64 * j];
;             const f32x4* sp = (const f32x4*)(ssq + (size_t)row * 32); f32x4 s = sp[0];
; #pragma unroll
;             for (int i = 1; i < 8; ++i) s += sp[i];
;             rs[u] = 1.0f / sqrtf(((s[0] + s[1]) + (s[2] + s[3])) * (1.0f / DM) + 1e-6f); }
; #pragma unroll
;         for (int u = 0; u < UR; ++u) { f32x4* xr = (f32x4*)(p.out + (size_t)(row0 + u * NGW) * DM) + lane;
; #pragma unroll
;             for (int j = 0; j < 8; ++j) __builtin_nontemporal_store(v[u][j] * rs[u] * g4[j], xr + 64 * j); } }
	v_pk_mul_f32 v[208:209], v[140:141], s[58:59] op_sel_hi:[1,0]
	v_pk_mul_f32 v[210:211], v[142:143], s[58:59] op_sel_hi:[1,0]
	v_pk_mul_f32 v[208:209], v[12:13], v[208:209]
	v_pk_mul_f32 v[210:211], v[14:15], v[210:211]
	global_store_dwordx4 v241, v[208:211], s[42:43] offset:3072 nt
	s_waitcnt vmcnt(58)
	v_pk_mul_f32 v[196:197], v[144:145], s[58:59] op_sel_hi:[1,0]
	v_pk_mul_f32 v[198:199], v[146:147], s[58:59] op_sel_hi:[1,0]
	v_pk_mul_f32 v[196:197], v[16:17], v[196:197]
	v_pk_mul_f32 v[198:199], v[18:19], v[198:199]
	global_store_dwordx4 v242, v[196:199], s[42:43] nt
	s_waitcnt vmcnt(58)
	v_pk_mul_f32 v[200:201], v[148:149], s[58:59] op_sel_hi:[1,0]
	v_pk_mul_f32 v[202:203], v[150:151], s[58:59] op_sel_hi:[1,0]
	v_pk_mul_f32 v[200:201], v[20:21], v[200:201]
	v_pk_mul_f32 v[202:203], v[22:23], v[202:203]
	global_store_dwordx4 v242, v[200:203], s[42:43] offset:1024 nt
	s_waitcnt vmcnt(58)
	v_pk_mul_f32 v[204:205], v[152:153], s[58:59] op_sel_hi:[1,0]
	v_pk_mul_f32 v[206:207], v[154:155], s[58:59] op_sel_hi:[1,0]
	v_pk_mul_f32 v[204:205], v[24:25], v[204:205]
	v_pk_mul_f32 v[206:207], v[26:27], v[206:207]
	global_store_dwordx4 v242, v[204:207], s[42:43] offset:2048 nt
	s_waitcnt vmcnt(58)
	v_pk_mul_f32 v[208:209], v[156:157], s[58:59] op_sel_hi:[1,0]
	v_pk_mul_f32 v[210:211], v[158:159], s[58:59] op_sel_hi:[1,0]
	v_pk_mul_f32 v[208:209], v[28:29], v[208:209]
	v_pk_mul_f32 v[210:211], v[30:31], v[210:211]
	global_store_dwordx4 v242, v[208:211], s[42:43] offset:3072 nt
	s_lshl_b32 s8, s7, 13
	s_add_u32 s50, s26, s8
	s_addc_u32 s51, s27, 0
	s_lshl_b32 s8, s7, 7
	s_add_u32 s74, s2, s8
	s_addc_u32 s75, s3, 0
	s_add_u32 s7, s7, s6
	global_load_dwordx4 v[172:175], v243, s[74:75]
	s_waitcnt vmcnt(52)
	global_load_dwordx4 v[128:131], v241, s[50:51]
	global_load_dwordx4 v[132:135], v241, s[50:51] offset:1024
	global_load_dwordx4 v[136:139], v241, s[50:51] offset:2048
	global_load_dwordx4 v[140:143], v241, s[50:51] offset:3072
	global_load_dwordx4 v[144:147], v242, s[50:51]
	global_load_dwordx4 v[148:151], v242, s[50:51] offset:1024
	global_load_dwordx4 v[152:155], v242, s[50:51] offset:2048
	global_load_dwordx4 v[156:159], v242, s[50:51] offset:3072
	s_waitcnt vmcnt(59)
	v_mov_b32_e32 v176, v160
	v_mov_b32_e32 v177, v161
	v_mov_b32_e32 v178, v162
	v_mov_b32_e32 v179, v163
	v_add_f32_dpp v176, v176, v160 row_shr:1 row_mask:0xf bank_mask:0xf
	v_add_f32_dpp v177, v177, v161 row_shr:1 row_mask:0xf bank_mask:0xf
	v_add_f32_dpp v178, v178, v162 row_shr:1 row_mask:0xf bank_mask:0xf
	v_add_f32_dpp v179, v179, v163 row_shr:1 row_mask:0xf bank_mask:0xf
	v_add_f32_dpp v176, v176, v160 row_shr:1 row_mask:0xf bank_mask:0xf
	v_add_f32_dpp v177, v177, v161 row_shr:1 row_mask:0xf bank_mask:0xf
	v_add_f32_dpp v178, v178, v162 row_shr:1 row_mask:0xf bank_mask:0xf
	v_add_f32_dpp v179, v179, v163 row_shr:1 row_mask:0xf bank_mask:0xf
	v_add_f32_dpp v176, v176, v160 row_shr:1 row_mask:0xf bank_mask:0xf
	v_add_f32_dpp v177, v177, v161 row_shr:1 row_mask:0xf bank_mask:0xf
	v_add_f32_dpp v178, v178, v162 row_shr:1 row_mask:0xf bank_mask:0xf
	v_add_f32_dpp v179, v179, v163 row_shr:1 row_mask:0xf bank_mask:0xf
	v_add_f32_dpp v176, v176, v160 row_shr:1 row_mask:0xf bank_mask:0xf
	v_add_f32_dpp v177, v177, v161 row_shr:1 row_mask:0xf bank_mask:0xf
	v_add_f32_dpp v178, v178, v162 row_shr:1 row_mask:0xf bank_mask:0xf
	v_add_f32_dpp v179, v179, v163 row_shr:1 row_mask:0xf bank_mask:0xf
	v_add_f32_dpp v176, v176, v160 row_shr:1 row_mask:0xf bank_mask:0xf
	v_add_f32_dpp v177, v177, v161 row_shr:1 row_mask:0xf bank_mask:0xf
	v_add_f32_dpp v178, v178, v162 row_shr:1 row_mask:0xf bank_mask:0xf
	v_add_f32_dpp v179, v179, v163 row_shr:1 row_mask:0xf bank_mask:0xf
	v_add_f32_dpp v176, v176, v160 row_shr:1 row_mask:0xf bank_mask:0xf
	v_add_f32_dpp v177, v177, v161 row_shr:1 row_mask:0xf bank_mask:0xf
	v_add_f32_dpp v178, v178, v162 row_shr:1 row_mask:0xf bank_mask:0xf
	v_add_f32_dpp v179, v179, v163 row_shr:1 row_mask:0xf bank_mask:0xf
	v_add_f32_dpp v176, v176, v160 row_shr:1 row_mask:0xf bank_mask:0xf
	v_add_f32_dpp v177, v177, v161 row_shr:1 row_mask:0xf bank_mask:0xf
	v_add_f32_dpp v178, v178, v162 row_shr:1 row_mask:0xf bank_mask:0xf
	v_add_f32_dpp v179, v179, v163 row_shr:1 row_mask:0xf bank_mask:0xf
	v_add_f32_e32 v227, v177, v176
	v_add_f32_e32 v229, v178, v179
	v_add_f32_e32 v212, v227, v229
	v_fmamk_f32 v213, v212, 0x3a000000, v232
	v_mul_f32_e32 v214, 0x4f800000, v213
	v_cmp_gt_f32_e32 vcc, s10, v213
	s_nop 1
	v_cndmask_b32_e32 v215, v213, v214, vcc
	v_sqrt_f32_e32 v216, v215
	s_nop 0
	v_add_u32_e32 v217, -1, v216
	v_add_u32_e32 v218, 1, v216
	v_fma_f32 v219, -v217, v216, v215
	v_fma_f32 v220, -v218, v216, v215
	v_cmp_ge_f32_e64 s[0:1], 0, v219
	s_nop 1
	v_cndmask_b32_e64 v221, v216, v217, s[0:1]
	v_cmp_lt_f32_e64 s[0:1], 0, v220
	s_nop 1
	v_cndmask_b32_e64 v221, v221, v218, s[0:1]
	v_mul_f32_e32 v222, 0x37800000, v221
	v_cndmask_b32_e32 v221, v221, v222, vcc
	v_cmp_class_f32_e32 vcc, v215, v233
	s_nop 1
	v_cndmask_b32_e32 v223, v221, v215, vcc
	v_div_scale_f32 v224, s[0:1], v223, v223, 1.0
	v_rcp_f32_e32 v225, v224
	v_div_scale_f32 v226, vcc, 1.0, v223, 1.0
	v_fma_f32 v227, -v224, v225, 1.0
	v_fmac_f32_e32 v225, v227, v225
	v_mul_f32_e32 v228, v226, v225
	v_fma_f32 v229, -v224, v228, v226
	v_fmac_f32_e32 v228, v229, v225
	v_fma_f32 v227, -v224, v228, v226
	v_div_fmas_f32 v230, v227, v225, v228
	v_div_fixup_f32 v231, v230, v223, 1.0
	s_nop 1
	v_readlane_b32 s52, v231, 7
	s_nop 1
	s_waitcnt vmcnt(58)
	v_pk_mul_f32 v[196:197], v[32:33], s[52:53] op_sel_hi:[1,0]
	v_pk_mul_f32 v[198:199], v[34:35], s[52:53] op_sel_hi:[1,0]
	v_pk_mul_f32 v[196:197], v[0:1], v[196:197]
	v_pk_mul_f32 v[198:199], v[2:3], v[198:199]
	global_store_dwordx4 v241, v[196:199], s[44:45] nt
	s_waitcnt vmcnt(58)
; __device__ __forceinline__ void phase_final(const Params& p) {
;     ...
;         for (int u = 0; u < UR; ++u) { const int row = row0 + u * NGW; const f32x4* xr = (const f32x4*)(p.out + (size_t)row * DM) + lane;
; #pragma unroll
;             for (int j = 0; j < 8; ++j) v[u][j] = xr[64 * j];
;             const f32x4* sp = (const f32x4*)(ssq + (size_t)row * 32); f32x4 s = sp[0];
; #pragma unroll
;             for (int i = 1; i < 8; ++i) s += sp[i];
;             rs[u] = 1.0f / sqrtf(((s[0] + s[1]) + (s[2] + s[3])) * (1.0f / DM) + 1e-6f); }
; #pragma unroll
;         for (int u = 0; u < UR; ++u) { f32x4* xr = (f32x4*)(p.out + (size_t)(row0 + u * NGW) * DM) + lane;
; #pragma unroll
;             for (int j = 0; j < 8; ++j) __builtin_nontemporal_store(v[u][j] * rs[u] * g4[j], xr + 64 * j); } }
	v_pk_mul_f32 v[200:201], v[36:37], s[52:53] op_sel_hi:[1,0]
	v_pk_mul_f32 v[202:203], v[38:39], s[52:53] op_sel_hi:[1,0]
	v_pk_mul_f32 v[200:201], v[4:5], v[200:201]
	v_pk_mul_f32 v[202:203], v[6:7], v[202:203]
	global_store_dwordx4 v241, v[200:203], s[44:45] offset:1024 nt
	s_waitcnt vmcnt(58)
	v_pk_mul_f32 v[204:205], v[40:41], s[52:53] op_sel_hi:[1,0]
	v_pk_mul_f32 v[206:207], v[42:43], s[52:53] op_sel_hi:[1,0]
	v_pk_mul_f32 v[204:205], v[8:9], v[204:205]
	v_pk_mul_f32 v[206:207], v[10:11], v[206:207]
	global_store_dwordx4 v241, v[204:207], s[44:45] offset:2048 nt
	s_waitcnt vmcnt(58)
	v_pk_mul_f32 v[208:209], v[44:45], s[52:53] op_sel_hi:[1,0]
	v_pk_mul_f32 v[210:211], v[46:47], s[52:53] op_sel_hi:[1,0]
	v_pk_mul_f32 v[208:209], v[12:13], v[208:209]
	v_pk_mul_f32 v[210:211], v[14:15], v[210:211]
	global_store_dwordx4 v241, v[208:211], s[44:45] offset:3072 nt
	s_waitcnt vmcnt(58)
	v_pk_mul_f32 v[196:197], v[48:49], s[52:53] op_sel_hi:[1,0]
	v_pk_mul_f32 v[198:199], v[50:51], s[52:53] op_sel_hi:[1,0]
	v_pk_mul_f32 v[196:197], v[16:17], v[196:197]
	v_pk_mul_f32 v[198:199], v[18:19], v[198:199]
	global_store_dwordx4 v242, v[196:199], s[44:45] nt
	s_waitcnt vmcnt(58)
	v_pk_mul_f32 v[200:201], v[52:53], s[52:53] op_sel_hi:[1,0]
	v_pk_mul_f32 v[202:203], v[54:55], s[52:53] op_sel_hi:[1,0]
	v_pk_mul_f32 v[200:201], v[20:21], v[200:201]
	v_pk_mul_f32 v[202:203], v[22:23], v[202:203]
	global_store_dwordx4 v242, v[200:203], s[44:45] offset:1024 nt
	s_waitcnt vmcnt(58)
	v_pk_mul_f32 v[204:205], v[56:57], s[52:53] op_sel_hi:[1,0]
	v_pk_mul_f32 v[206:207], v[58:59], s[52:53] op_sel_hi:[1,0]
	v_pk_mul_f32 v[204:205], v[24:25], v[204:205]
	v_pk_mul_f32 v[206:207], v[26:27], v[206:207]
	global_store_dwordx4 v242, v[204:207], s[44:45] offset:2048 nt
	s_waitcnt vmcnt(58)
	v_pk_mul_f32 v[208:209], v[60:61], s[52:53] op_sel_hi:[1,0]
	v_pk_mul_f32 v[210:211], v[62:63], s[52:53] op_sel_hi:[1,0]
	v_pk_mul_f32 v[208:209], v[28:29], v[208:209]
	v_pk_mul_f32 v[210:211], v[30:31], v[210:211]
	global_store_dwordx4 v242, v[208:211], s[44:45] offset:3072 nt
	s_lshl_b32 s8, s7, 13
	s_add_u32 s36, s26, s8
	s_addc_u32 s37, s27, 0
	s_lshl_b32 s8, s7, 7
	s_add_u32 s60, s2, s8
	s_addc_u32 s61, s3, 0
	s_add_u32 s7, s7, s6
	global_load_dwordx4 v[160:163], v243, s[60:61]
	s_waitcnt vmcnt(52)
	global_load_dwordx4 v[32:35], v241, s[36:37]
	global_load_dwordx4 v[36:39], v241, s[36:37] offset:1024
	global_load_dwordx4 v[40:43], v241, s[36:37] offset:2048
	global_load_dwordx4 v[44:47], v241, s[36:37] offset:3072
	global_load_dwordx4 v[48:51], v242, s[36:37]
	global_load_dwordx4 v[52:55], v242, s[36:37] offset:1024
	global_load_dwordx4 v[56:59], v242, s[36:37] offset:2048
	global_load_dwordx4 v[60:63], v242, s[36:37] offset:3072
	s_waitcnt vmcnt(59)
	v_mov_b32_e32 v180, v164
	v_mov_b32_e32 v181, v165
	v_mov_b32_e32 v182, v166
	v_mov_b32_e32 v183, v167
	v_add_f32_dpp v180, v180, v164 row_shr:1 row_mask:0xf bank_mask:0xf
	v_add_f32_dpp v181, v181, v165 row_shr:1 row_mask:0xf bank_mask:0xf
	v_add_f32_dpp v182, v182, v166 row_shr:1 row_mask:0xf bank_mask:0xf
	v_add_f32_dpp v183, v183, v167 row_shr:1 row_mask:0xf bank_mask:0xf
	v_add_f32_dpp v180, v180, v164 row_shr:1 row_mask:0xf bank_mask:0xf
	v_add_f32_dpp v181, v181, v165 row_shr:1 row_mask:0xf bank_mask:0xf
	v_add_f32_dpp v182, v182, v166 row_shr:1 row_mask:0xf bank_mask:0xf
	v_add_f32_dpp v183, v183, v167 row_shr:1 row_mask:0xf bank_mask:0xf
	v_add_f32_dpp v180, v180, v164 row_shr:1 row_mask:0xf bank_mask:0xf
	v_add_f32_dpp v181, v181, v165 row_shr:1 row_mask:0xf bank_mask:0xf
	v_add_f32_dpp v182, v182, v166 row_shr:1 row_mask:0xf bank_mask:0xf
	v_add_f32_dpp v183, v183, v167 row_shr:1 row_mask:0xf bank_mask:0xf
	v_add_f32_dpp v180, v180, v164 row_shr:1 row_mask:0xf bank_mask:0xf
	v_add_f32_dpp v181, v181, v165 row_shr:1 row_mask:0xf bank_mask:0xf
	v_add_f32_dpp v182, v182, v166 row_shr:1 row_mask:0xf bank_mask:0xf
	v_add_f32_dpp v183, v183, v167 row_shr:1 row_mask:0xf bank_mask:0xf
	v_add_f32_dpp v180, v180, v164 row_shr:1 row_mask:0xf bank_mask:0xf
	v_add_f32_dpp v181, v181, v165 row_shr:1 row_mask:0xf bank_mask:0xf
	v_add_f32_dpp v182, v182, v166 row_shr:1 row_mask:0xf bank_mask:0xf
	v_add_f32_dpp v183, v183, v167 row_shr:1 row_mask:0xf bank_mask:0xf
	v_add_f32_dpp v180, v180, v164 row_shr:1 row_mask:0xf bank_mask:0xf
	v_add_f32_dpp v181, v181, v165 row_shr:1 row_mask:0xf bank_mask:0xf
	v_add_f32_dpp v182, v182, v166 row_shr:1 row_mask:0xf bank_mask:0xf
	v_add_f32_dpp v183, v183, v167 row_shr:1 row_mask:0xf bank_mask:0xf
	v_add_f32_dpp v180, v180, v164 row_shr:1 row_mask:0xf bank_mask:0xf
	v_add_f32_dpp v181, v181, v165 row_shr:1 row_mask:0xf bank_mask:0xf
	v_add_f32_dpp v182, v182, v166 row_shr:1 row_mask:0xf bank_mask:0xf
	v_add_f32_dpp v183, v183, v167 row_shr:1 row_mask:0xf bank_mask:0xf
	v_add_f32_e32 v227, v181, v180
	v_add_f32_e32 v229, v182, v183
	v_add_f32_e32 v212, v227, v229
	v_fmamk_f32 v213, v212, 0x3a000000, v232
	v_mul_f32_e32 v214, 0x4f800000, v213
	v_cmp_gt_f32_e32 vcc, s10, v213
	s_nop 1
	v_cndmask_b32_e32 v215, v213, v214, vcc
	v_sqrt_f32_e32 v216, v215
	s_nop 0
	v_add_u32_e32 v217, -1, v216
	v_add_u32_e32 v218, 1, v216
	v_fma_f32 v219, -v217, v216, v215
	v_fma_f32 v220, -v218, v216, v215
	v_cmp_ge_f32_e64 s[0:1], 0, v219
	s_nop 1
	v_cndmask_b32_e64 v221, v216, v217, s[0:1]
	v_cmp_lt_f32_e64 s[0:1], 0, v220
	s_nop 1
	v_cndmask_b32_e64 v221, v221, v218, s[0:1]
	v_mul_f32_e32 v222, 0x37800000, v221
	v_cndmask_b32_e32 v221, v221, v222, vcc
	v_cmp_class_f32_e32 vcc, v215, v233
	s_nop 1
	v_cndmask_b32_e32 v223, v221, v215, vcc
	v_div_scale_f32 v224, s[0:1], v223, v223, 1.0
	v_rcp_f32_e32 v225, v224
	v_div_scale_f32 v226, vcc, 1.0, v223, 1.0
	v_fma_f32 v227, -v224, v225, 1.0
	v_fmac_f32_e32 v225, v227, v225
	v_mul_f32_e32 v228, v226, v225
	v_fma_f32 v229, -v224, v228, v226
	v_fmac_f32_e32 v228, v229, v225
	v_fma_f32 v227, -v224, v228, v226
	v_div_fmas_f32 v230, v227, v225, v228
	v_div_fixup_f32 v231, v230, v223, 1.0
	s_nop 1
	v_readlane_b32 s54, v231, 7
	s_nop 1
	s_waitcnt vmcnt(58)
; __device__ __forceinline__ void phase_final(const Params& p) {
;     ...
;         for (int u = 0; u < UR; ++u) { const int row = row0 + u * NGW; const f32x4* xr = (const f32x4*)(p.out + (size_t)row * DM) + lane;
; #pragma unroll
;             for (int j = 0; j < 8; ++j) v[u][j] = xr[64 * j];
;             const f32x4* sp = (const f32x4*)(ssq + (size_t)row * 32); f32x4 s = sp[0];
; #pragma unroll
;             for (int i = 1; i < 8; ++i) s += sp[i];
;             rs[u] = 1.0f / sqrtf(((s[0] + s[1]) + (s[2] + s[3])) * (1.0f / DM) + 1e-6f); }
; #pragma unroll
;         for (int u = 0; u < UR; ++u) { f32x4* xr = (f32x4*)(p.out + (size_t)(row0 + u * NGW) * DM) + lane;
; #pragma unroll
;             for (int j = 0; j < 8; ++j) __builtin_nontemporal_store(v[u][j] * rs[u] * g4[j], xr + 64 * j); } }
	v_pk_mul_f32 v[196:197], v[64:65], s[54:55] op_sel_hi:[1,0]
	v_pk_mul_f32 v[198:199], v[66:67], s[54:55] op_sel_hi:[1,0]
	v_pk_mul_f32 v[196:197], v[0:1], v[196:197]
	v_pk_mul_f32 v[198:199], v[2:3], v[198:199]
	global_store_dwordx4 v241, v[196:199], s[46:47] nt
	s_waitcnt vmcnt(58)
	v_pk_mul_f32 v[200:201], v[68:69], s[54:55] op_sel_hi:[1,0]
	v_pk_mul_f32 v[202:203], v[70:71], s[54:55] op_sel_hi:[1,0]
	v_pk_mul_f32 v[200:201], v[4:5], v[200:201]
	v_pk_mul_f32 v[202:203], v[6:7], v[202:203]
	global_store_dwordx4 v241, v[200:203], s[46:47] offset:1024 nt
	s_waitcnt vmcnt(58)
	v_pk_mul_f32 v[204:205], v[72:73], s[54:55] op_sel_hi:[1,0]
	v_pk_mul_f32 v[206:207], v[74:75], s[54:55] op_sel_hi:[1,0]
	v_pk_mul_f32 v[204:205], v[8:9], v[204:205]
	v_pk_mul_f32 v[206:207], v[10:11], v[206:207]
	global_store_dwordx4 v241, v[204:207], s[46:47] offset:2048 nt
	s_waitcnt vmcnt(58)
	v_pk_mul_f32 v[208:209], v[76:77], s[54:55] op_sel_hi:[1,0]
	v_pk_mul_f32 v[210:211], v[78:79], s[54:55] op_sel_hi:[1,0]
	v_pk_mul_f32 v[208:209], v[12:13], v[208:209]
	v_pk_mul_f32 v[210:211], v[14:15], v[210:211]
	global_store_dwordx4 v241, v[208:211], s[46:47] offset:3072 nt
	s_waitcnt vmcnt(58)
	v_pk_mul_f32 v[196:197], v[80:81], s[54:55] op_sel_hi:[1,0]
	v_pk_mul_f32 v[198:199], v[82:83], s[54:55] op_sel_hi:[1,0]
	v_pk_mul_f32 v[196:197], v[16:17], v[196:197]
	v_pk_mul_f32 v[198:199], v[18:19], v[198:199]
	global_store_dwordx4 v242, v[196:199], s[46:47] nt
	s_waitcnt vmcnt(58)
	v_pk_mul_f32 v[200:201], v[84:85], s[54:55] op_sel_hi:[1,0]
	v_pk_mul_f32 v[202:203], v[86:87], s[54:55] op_sel_hi:[1,0]
	v_pk_mul_f32 v[200:201], v[20:21], v[200:201]
	v_pk_mul_f32 v[202:203], v[22:23], v[202:203]
	global_store_dwordx4 v242, v[200:203], s[46:47] offset:1024 nt
	s_waitcnt vmcnt(58)
	v_pk_mul_f32 v[204:205], v[88:89], s[54:55] op_sel_hi:[1,0]
	v_pk_mul_f32 v[206:207], v[90:91], s[54:55] op_sel_hi:[1,0]
	v_pk_mul_f32 v[204:205], v[24:25], v[204:205]
	v_pk_mul_f32 v[206:207], v[26:27], v[206:207]
	global_store_dwordx4 v242, v[204:207], s[46:47] offset:2048 nt
	s_waitcnt vmcnt(58)
	v_pk_mul_f32 v[208:209], v[92:93], s[54:55] op_sel_hi:[1,0]
	v_pk_mul_f32 v[210:211], v[94:95], s[54:55] op_sel_hi:[1,0]
	v_pk_mul_f32 v[208:209], v[28:29], v[208:209]
	v_pk_mul_f32 v[210:211], v[30:31], v[210:211]
	global_store_dwordx4 v242, v[208:211], s[46:47] offset:3072 nt
	s_lshl_b32 s8, s7, 13
	s_add_u32 s38, s26, s8
	s_addc_u32 s39, s27, 0
	s_lshl_b32 s8, s7, 7
	s_add_u32 s62, s2, s8
	s_addc_u32 s63, s3, 0
	s_add_u32 s7, s7, s6
	global_load_dwordx4 v[164:167], v243, s[62:63]
	s_waitcnt vmcnt(52)
	global_load_dwordx4 v[64:67], v241, s[38:39]
	global_load_dwordx4 v[68:71], v241, s[38:39] offset:1024
	global_load_dwordx4 v[72:75], v241, s[38:39] offset:2048
	global_load_dwordx4 v[76:79], v241, s[38:39] offset:3072
	global_load_dwordx4 v[80:83], v242, s[38:39]
	global_load_dwordx4 v[84:87], v242, s[38:39] offset:1024
	global_load_dwordx4 v[88:91], v242, s[38:39] offset:2048
	global_load_dwordx4 v[92:95], v242, s[38:39] offset:3072
	s_waitcnt vmcnt(59)
	v_mov_b32_e32 v184, v168
	v_mov_b32_e32 v185, v169
	v_mov_b32_e32 v186, v170
	v_mov_b32_e32 v187, v171
	v_add_f32_dpp v184, v184, v168 row_shr:1 row_mask:0xf bank_mask:0xf
	v_add_f32_dpp v185, v185, v169 row_shr:1 row_mask:0xf bank_mask:0xf
	v_add_f32_dpp v186, v186, v170 row_shr:1 row_mask:0xf bank_mask:0xf
	v_add_f32_dpp v187, v187, v171 row_shr:1 row_mask:0xf bank_mask:0xf
	v_add_f32_dpp v184, v184, v168 row_shr:1 row_mask:0xf bank_mask:0xf
	v_add_f32_dpp v185, v185, v169 row_shr:1 row_mask:0xf bank_mask:0xf
	v_add_f32_dpp v186, v186, v170 row_shr:1 row_mask:0xf bank_mask:0xf
	v_add_f32_dpp v187, v187, v171 row_shr:1 row_mask:0xf bank_mask:0xf
	v_add_f32_dpp v184, v184, v168 row_shr:1 row_mask:0xf bank_mask:0xf
	v_add_f32_dpp v185, v185, v169 row_shr:1 row_mask:0xf bank_mask:0xf
	v_add_f32_dpp v186, v186, v170 row_shr:1 row_mask:0xf bank_mask:0xf
	v_add_f32_dpp v187, v187, v171 row_shr:1 row_mask:0xf bank_mask:0xf
	v_add_f32_dpp v184, v184, v168 row_shr:1 row_mask:0xf bank_mask:0xf
	v_add_f32_dpp v185, v185, v169 row_shr:1 row_mask:0xf bank_mask:0xf
	v_add_f32_dpp v186, v186, v170 row_shr:1 row_mask:0xf bank_mask:0xf
	v_add_f32_dpp v187, v187, v171 row_shr:1 row_mask:0xf bank_mask:0xf
	v_add_f32_dpp v184, v184, v168 row_shr:1 row_mask:0xf bank_mask:0xf
	v_add_f32_dpp v185, v185, v169 row_shr:1 row_mask:0xf bank_mask:0xf
	v_add_f32_dpp v186, v186, v170 row_shr:1 row_mask:0xf bank_mask:0xf
	v_add_f32_dpp v187, v187, v171 row_shr:1 row_mask:0xf bank_mask:0xf
	v_add_f32_dpp v184, v184, v168 row_shr:1 row_mask:0xf bank_mask:0xf
	v_add_f32_dpp v185, v185, v169 row_shr:1 row_mask:0xf bank_mask:0xf
	v_add_f32_dpp v186, v186, v170 row_shr:1 row_mask:0xf bank_mask:0xf
	v_add_f32_dpp v187, v187, v171 row_shr:1 row_mask:0xf bank_mask:0xf
	v_add_f32_dpp v184, v184, v168 row_shr:1 row_mask:0xf bank_mask:0xf
	v_add_f32_dpp v185, v185, v169 row_shr:1 row_mask:0xf bank_mask:0xf
	v_add_f32_dpp v186, v186, v170 row_shr:1 row_mask:0xf bank_mask:0xf
	v_add_f32_dpp v187, v187, v171 row_shr:1 row_mask:0xf bank_mask:0xf
	v_add_f32_e32 v227, v185, v184
	v_add_f32_e32 v229, v186, v187
	v_add_f32_e32 v212, v227, v229
	v_fmamk_f32 v213, v212, 0x3a000000, v232
	v_mul_f32_e32 v214, 0x4f800000, v213
	v_cmp_gt_f32_e32 vcc, s10, v213
	s_nop 1
	v_cndmask_b32_e32 v215, v213, v214, vcc
	v_sqrt_f32_e32 v216, v215
	s_nop 0
	v_add_u32_e32 v217, -1, v216
	v_add_u32_e32 v218, 1, v216
	v_fma_f32 v219, -v217, v216, v215
	v_fma_f32 v220, -v218, v216, v215
	v_cmp_ge_f32_e64 s[0:1], 0, v219
	s_nop 1
	v_cndmask_b32_e64 v221, v216, v217, s[0:1]
	v_cmp_lt_f32_e64 s[0:1], 0, v220
	s_nop 1
	v_cndmask_b32_e64 v221, v221, v218, s[0:1]
	v_mul_f32_e32 v222, 0x37800000, v221
	v_cndmask_b32_e32 v221, v221, v222, vcc
	v_cmp_class_f32_e32 vcc, v215, v233
	s_nop 1
	v_cndmask_b32_e32 v223, v221, v215, vcc
	v_div_scale_f32 v224, s[0:1], v223, v223, 1.0
	v_rcp_f32_e32 v225, v224
	v_div_scale_f32 v226, vcc, 1.0, v223, 1.0
	v_fma_f32 v227, -v224, v225, 1.0
	v_fmac_f32_e32 v225, v227, v225
	v_mul_f32_e32 v228, v226, v225
	v_fma_f32 v229, -v224, v228, v226
	v_fmac_f32_e32 v228, v229, v225
	v_fma_f32 v227, -v224, v228, v226
	v_div_fmas_f32 v230, v227, v225, v228
	v_div_fixup_f32 v231, v230, v223, 1.0
	s_nop 1
	v_readlane_b32 s56, v231, 7
	s_nop 1
	s_waitcnt vmcnt(58)
; __device__ __forceinline__ void phase_final(const Params& p) {
;     ...
;         for (int u = 0; u < UR; ++u) { const int row = row0 + u * NGW; const f32x4* xr = (const f32x4*)(p.out + (size_t)row * DM) + lane;
; #pragma unroll
;             for (int j = 0; j < 8; ++j) v[u][j] = xr[64 * j];
;             const f32x4* sp = (const f32x4*)(ssq + (size_t)row * 32); f32x4 s = sp[0];
; #pragma unroll
;             for (int i = 1; i < 8; ++i) s += sp[i];
;             rs[u] = 1.0f / sqrtf(((s[0] + s[1]) + (s[2] + s[3])) * (1.0f / DM) + 1e-6f); }
; #pragma unroll
;         for (int u = 0; u < UR; ++u) { f32x4* xr = (f32x4*)(p.out + (size_t)(row0 + u * NGW) * DM) + lane;
; #pragma unroll
;             for (int j = 0; j < 8; ++j) __builtin_nontemporal_store(v[u][j] * rs[u] * g4[j], xr + 64 * j); } }
	v_pk_mul_f32 v[196:197], v[96:97], s[56:57] op_sel_hi:[1,0]
	v_pk_mul_f32 v[198:199], v[98:99], s[56:57] op_sel_hi:[1,0]
	v_pk_mul_f32 v[196:197], v[0:1], v[196:197]
	v_pk_mul_f32 v[198:199], v[2:3], v[198:199]
	global_store_dwordx4 v241, v[196:199], s[48:49] nt
	s_waitcnt vmcnt(58)
	v_pk_mul_f32 v[200:201], v[100:101], s[56:57] op_sel_hi:[1,0]
	v_pk_mul_f32 v[202:203], v[102:103], s[56:57] op_sel_hi:[1,0]
	v_pk_mul_f32 v[200:201], v[4:5], v[200:201]
	v_pk_mul_f32 v[202:203], v[6:7], v[202:203]
	global_store_dwordx4 v241, v[200:203], s[48:49] offset:1024 nt
	s_waitcnt vmcnt(58)
	v_pk_mul_f32 v[204:205], v[104:105], s[56:57] op_sel_hi:[1,0]
	v_pk_mul_f32 v[206:207], v[106:107], s[56:57] op_sel_hi:[1,0]
	v_pk_mul_f32 v[204:205], v[8:9], v[204:205]
	v_pk_mul_f32 v[206:207], v[10:11], v[206:207]
	global_store_dwordx4 v241, v[204:207], s[48:49] offset:2048 nt
	s_waitcnt vmcnt(58)
	v_pk_mul_f32 v[208:209], v[108:109], s[56:57] op_sel_hi:[1,0]
	v_pk_mul_f32 v[210:211], v[110:111], s[56:57] op_sel_hi:[1,0]
	v_pk_mul_f32 v[208:209], v[12:13], v[208:209]
	v_pk_mul_f32 v[210:211], v[14:15], v[210:211]
	global_store_dwordx4 v241, v[208:211], s[48:49] offset:3072 nt
	s_waitcnt vmcnt(58)
	v_pk_mul_f32 v[196:197], v[112:113], s[56:57] op_sel_hi:[1,0]
	v_pk_mul_f32 v[198:199], v[114:115], s[56:57] op_sel_hi:[1,0]
	v_pk_mul_f32 v[196:197], v[16:17], v[196:197]
	v_pk_mul_f32 v[198:199], v[18:19], v[198:199]
	global_store_dwordx4 v242, v[196:199], s[48:49] nt
	s_waitcnt vmcnt(58)
	v_pk_mul_f32 v[200:201], v[116:117], s[56:57] op_sel_hi:[1,0]
	v_pk_mul_f32 v[202:203], v[118:119], s[56:57] op_sel_hi:[1,0]
	v_pk_mul_f32 v[200:201], v[20:21], v[200:201]
	v_pk_mul_f32 v[202:203], v[22:23], v[202:203]
	global_store_dwordx4 v242, v[200:203], s[48:49] offset:1024 nt
	s_waitcnt vmcnt(58)
	v_pk_mul_f32 v[204:205], v[120:121], s[56:57] op_sel_hi:[1,0]
	v_pk_mul_f32 v[206:207], v[122:123], s[56:57] op_sel_hi:[1,0]
	v_pk_mul_f32 v[204:205], v[24:25], v[204:205]
	v_pk_mul_f32 v[206:207], v[26:27], v[206:207]
	global_store_dwordx4 v242, v[204:207], s[48:49] offset:2048 nt
	s_waitcnt vmcnt(58)
	v_pk_mul_f32 v[208:209], v[124:125], s[56:57] op_sel_hi:[1,0]
	v_pk_mul_f32 v[210:211], v[126:127], s[56:57] op_sel_hi:[1,0]
	v_pk_mul_f32 v[208:209], v[28:29], v[208:209]
	v_pk_mul_f32 v[210:211], v[30:31], v[210:211]
	global_store_dwordx4 v242, v[208:211], s[48:49] offset:3072 nt
	s_lshl_b32 s8, s7, 13
	s_add_u32 s40, s26, s8
	s_addc_u32 s41, s27, 0
	s_lshl_b32 s8, s7, 7
	s_add_u32 s64, s2, s8
	s_addc_u32 s65, s3, 0
	s_add_u32 s7, s7, s6
	global_load_dwordx4 v[168:171], v243, s[64:65]
	s_waitcnt vmcnt(52)
	global_load_dwordx4 v[96:99], v241, s[40:41]
	global_load_dwordx4 v[100:103], v241, s[40:41] offset:1024
	global_load_dwordx4 v[104:107], v241, s[40:41] offset:2048
	global_load_dwordx4 v[108:111], v241, s[40:41] offset:3072
	global_load_dwordx4 v[112:115], v242, s[40:41]
	global_load_dwordx4 v[116:119], v242, s[40:41] offset:1024
	global_load_dwordx4 v[120:123], v242, s[40:41] offset:2048
	global_load_dwordx4 v[124:127], v242, s[40:41] offset:3072
	s_waitcnt vmcnt(59)
	v_mov_b32_e32 v188, v172
	v_mov_b32_e32 v189, v173
	v_mov_b32_e32 v190, v174
	v_mov_b32_e32 v191, v175
	v_add_f32_dpp v188, v188, v172 row_shr:1 row_mask:0xf bank_mask:0xf
	v_add_f32_dpp v189, v189, v173 row_shr:1 row_mask:0xf bank_mask:0xf
	v_add_f32_dpp v190, v190, v174 row_shr:1 row_mask:0xf bank_mask:0xf
	v_add_f32_dpp v191, v191, v175 row_shr:1 row_mask:0xf bank_mask:0xf
	v_add_f32_dpp v188, v188, v172 row_shr:1 row_mask:0xf bank_mask:0xf
	v_add_f32_dpp v189, v189, v173 row_shr:1 row_mask:0xf bank_mask:0xf
	v_add_f32_dpp v190, v190, v174 row_shr:1 row_mask:0xf bank_mask:0xf
	v_add_f32_dpp v191, v191, v175 row_shr:1 row_mask:0xf bank_mask:0xf
	v_add_f32_dpp v188, v188, v172 row_shr:1 row_mask:0xf bank_mask:0xf
	v_add_f32_dpp v189, v189, v173 row_shr:1 row_mask:0xf bank_mask:0xf
	v_add_f32_dpp v190, v190, v174 row_shr:1 row_mask:0xf bank_mask:0xf
	v_add_f32_dpp v191, v191, v175 row_shr:1 row_mask:0xf bank_mask:0xf
	v_add_f32_dpp v188, v188, v172 row_shr:1 row_mask:0xf bank_mask:0xf
	v_add_f32_dpp v189, v189, v173 row_shr:1 row_mask:0xf bank_mask:0xf
	v_add_f32_dpp v190, v190, v174 row_shr:1 row_mask:0xf bank_mask:0xf
	v_add_f32_dpp v191, v191, v175 row_shr:1 row_mask:0xf bank_mask:0xf
	v_add_f32_dpp v188, v188, v172 row_shr:1 row_mask:0xf bank_mask:0xf
	v_add_f32_dpp v189, v189, v173 row_shr:1 row_mask:0xf bank_mask:0xf
	v_add_f32_dpp v190, v190, v174 row_shr:1 row_mask:0xf bank_mask:0xf
	v_add_f32_dpp v191, v191, v175 row_shr:1 row_mask:0xf bank_mask:0xf
	v_add_f32_dpp v188, v188, v172 row_shr:1 row_mask:0xf bank_mask:0xf
	v_add_f32_dpp v189, v189, v173 row_shr:1 row_mask:0xf bank_mask:0xf
	v_add_f32_dpp v190, v190, v174 row_shr:1 row_mask:0xf bank_mask:0xf
	v_add_f32_dpp v191, v191, v175 row_shr:1 row_mask:0xf bank_mask:0xf
	v_add_f32_dpp v188, v188, v172 row_shr:1 row_mask:0xf bank_mask:0xf
	v_add_f32_dpp v189, v189, v173 row_shr:1 row_mask:0xf bank_mask:0xf
	v_add_f32_dpp v190, v190, v174 row_shr:1 row_mask:0xf bank_mask:0xf
	v_add_f32_dpp v191, v191, v175 row_shr:1 row_mask:0xf bank_mask:0xf
	v_add_f32_e32 v227, v189, v188
	v_add_f32_e32 v229, v190, v191
	v_add_f32_e32 v212, v227, v229
	v_fmamk_f32 v213, v212, 0x3a000000, v232
	v_mul_f32_e32 v214, 0x4f800000, v213
	v_cmp_gt_f32_e32 vcc, s10, v213
	s_nop 1
	v_cndmask_b32_e32 v215, v213, v214, vcc
	v_sqrt_f32_e32 v216, v215
	s_nop 0
	v_add_u32_e32 v217, -1, v216
	v_add_u32_e32 v218, 1, v216
	v_fma_f32 v219, -v217, v216, v215
	v_fma_f32 v220, -v218, v216, v215
	v_cmp_ge_f32_e64 s[0:1], 0, v219
	s_nop 1
	v_cndmask_b32_e64 v221, v216, v217, s[0:1]
	v_cmp_lt_f32_e64 s[0:1], 0, v220
	s_nop 1
	v_cndmask_b32_e64 v221, v221, v218, s[0:1]
	v_mul_f32_e32 v222, 0x37800000, v221
	v_cndmask_b32_e32 v221, v221, v222, vcc
	v_cmp_class_f32_e32 vcc, v215, v233
	s_nop 1
	v_cndmask_b32_e32 v223, v221, v215, vcc
	v_div_scale_f32 v224, s[0:1], v223, v223, 1.0
	v_rcp_f32_e32 v225, v224
	v_div_scale_f32 v226, vcc, 1.0, v223, 1.0
	v_fma_f32 v227, -v224, v225, 1.0
	v_fmac_f32_e32 v225, v227, v225
	v_mul_f32_e32 v228, v226, v225
	v_fma_f32 v229, -v224, v228, v226
	v_fmac_f32_e32 v228, v229, v225
	v_fma_f32 v227, -v224, v228, v226
	v_div_fmas_f32 v230, v227, v225, v228
	v_div_fixup_f32 v231, v230, v223, 1.0
	s_nop 1
	v_readlane_b32 s58, v231, 7
	s_nop 1
	s_waitcnt vmcnt(58)
; __device__ __forceinline__ void phase_final(const Params& p) {
;     ...
;         for (int u = 0; u < UR; ++u) { const int row = row0 + u * NGW; const f32x4* xr = (const f32x4*)(p.out + (size_t)row * DM) + lane;
; #pragma unroll
;             for (int j = 0; j < 8; ++j) v[u][j] = xr[64 * j];
;             const f32x4* sp = (const f32x4*)(ssq + (size_t)row * 32); f32x4 s = sp[0];
; #pragma unroll
;             for (int i = 1; i < 8; ++i) s += sp[i];
;             rs[u] = 1.0f / sqrtf(((s[0] + s[1]) + (s[2] + s[3])) * (1.0f / DM) + 1e-6f); }
; #pragma unroll
;         for (int u = 0; u < UR; ++u) { f32x4* xr = (f32x4*)(p.out + (size_t)(row0 + u * NGW) * DM) + lane;
; #pragma unroll
;             for (int j = 0; j < 8; ++j) __builtin_nontemporal_store(v[u][j] * rs[u] * g4[j], xr + 64 * j); } }
	v_pk_mul_f32 v[196:197], v[128:129], s[58:59] op_sel_hi:[1,0]
	v_pk_mul_f32 v[198:199], v[130:131], s[58:59] op_sel_hi:[1,0]
	v_pk_mul_f32 v[196:197], v[0:1], v[196:197]
	v_pk_mul_f32 v[198:199], v[2:3], v[198:199]
	global_store_dwordx4 v241, v[196:199], s[50:51] nt
	s_waitcnt vmcnt(58)
	v_pk_mul_f32 v[200:201], v[132:133], s[58:59] op_sel_hi:[1,0]
	v_pk_mul_f32 v[202:203], v[134:135], s[58:59] op_sel_hi:[1,0]
	v_pk_mul_f32 v[200:201], v[4:5], v[200:201]
	v_pk_mul_f32 v[202:203], v[6:7], v[202:203]
	global_store_dwordx4 v241, v[200:203], s[50:51] offset:1024 nt
	s_waitcnt vmcnt(58)
	v_pk_mul_f32 v[204:205], v[136:137], s[58:59] op_sel_hi:[1,0]
	v_pk_mul_f32 v[206:207], v[138:139], s[58:59] op_sel_hi:[1,0]
	v_pk_mul_f32 v[204:205], v[8:9], v[204:205]
	v_pk_mul_f32 v[206:207], v[10:11], v[206:207]
	global_store_dwordx4 v241, v[204:207], s[50:51] offset:2048 nt
	s_waitcnt vmcnt(58)
	v_pk_mul_f32 v[208:209], v[140:141], s[58:59] op_sel_hi:[1,0]
	v_pk_mul_f32 v[210:211], v[142:143], s[58:59] op_sel_hi:[1,0]
	v_pk_mul_f32 v[208:209], v[12:13], v[208:209]
	v_pk_mul_f32 v[210:211], v[14:15], v[210:211]
	global_store_dwordx4 v241, v[208:211], s[50:51] offset:3072 nt
	s_waitcnt vmcnt(58)
	v_pk_mul_f32 v[196:197], v[144:145], s[58:59] op_sel_hi:[1,0]
	v_pk_mul_f32 v[198:199], v[146:147], s[58:59] op_sel_hi:[1,0]
	v_pk_mul_f32 v[196:197], v[16:17], v[196:197]
	v_pk_mul_f32 v[198:199], v[18:19], v[198:199]
	global_store_dwordx4 v242, v[196:199], s[50:51] nt
	s_waitcnt vmcnt(58)
	v_pk_mul_f32 v[200:201], v[148:149], s[58:59] op_sel_hi:[1,0]
	v_pk_mul_f32 v[202:203], v[150:151], s[58:59] op_sel_hi:[1,0]
	v_pk_mul_f32 v[200:201], v[20:21], v[200:201]
	v_pk_mul_f32 v[202:203], v[22:23], v[202:203]
	global_store_dwordx4 v242, v[200:203], s[50:51] offset:1024 nt
	s_waitcnt vmcnt(58)
	v_pk_mul_f32 v[204:205], v[152:153], s[58:59] op_sel_hi:[1,0]
	v_pk_mul_f32 v[206:207], v[154:155], s[58:59] op_sel_hi:[1,0]
	v_pk_mul_f32 v[204:205], v[24:25], v[204:205]
	v_pk_mul_f32 v[206:207], v[26:27], v[206:207]
	global_store_dwordx4 v242, v[204:207], s[50:51] offset:2048 nt
	s_waitcnt vmcnt(58)
	v_pk_mul_f32 v[208:209], v[156:157], s[58:59] op_sel_hi:[1,0]
	v_pk_mul_f32 v[210:211], v[158:159], s[58:59] op_sel_hi:[1,0]
	v_pk_mul_f32 v[208:209], v[28:29], v[208:209]
	v_pk_mul_f32 v[210:211], v[30:31], v[210:211]
	global_store_dwordx4 v242, v[208:211], s[50:51] offset:3072 nt
	s_lshl_b32 s8, s7, 13
	s_add_u32 s42, s26, s8
	s_addc_u32 s43, s27, 0
	s_lshl_b32 s8, s7, 7
	s_add_u32 s66, s2, s8
	s_addc_u32 s67, s3, 0
	s_add_u32 s7, s7, s6
	global_load_dwordx4 v[172:175], v243, s[66:67]
	s_waitcnt vmcnt(52)
	global_load_dwordx4 v[128:131], v241, s[42:43]
	global_load_dwordx4 v[132:135], v241, s[42:43] offset:1024
	global_load_dwordx4 v[136:139], v241, s[42:43] offset:2048
	global_load_dwordx4 v[140:143], v241, s[42:43] offset:3072
	global_load_dwordx4 v[144:147], v242, s[42:43]
	global_load_dwordx4 v[148:151], v242, s[42:43] offset:1024
	global_load_dwordx4 v[152:155], v242, s[42:43] offset:2048
	global_load_dwordx4 v[156:159], v242, s[42:43] offset:3072
	s_waitcnt vmcnt(59)
	v_mov_b32_e32 v176, v160
	v_mov_b32_e32 v177, v161
	v_mov_b32_e32 v178, v162
	v_mov_b32_e32 v179, v163
	v_add_f32_dpp v176, v176, v160 row_shr:1 row_mask:0xf bank_mask:0xf
	v_add_f32_dpp v177, v177, v161 row_shr:1 row_mask:0xf bank_mask:0xf
	v_add_f32_dpp v178, v178, v162 row_shr:1 row_mask:0xf bank_mask:0xf
	v_add_f32_dpp v179, v179, v163 row_shr:1 row_mask:0xf bank_mask:0xf
	v_add_f32_dpp v176, v176, v160 row_shr:1 row_mask:0xf bank_mask:0xf
	v_add_f32_dpp v177, v177, v161 row_shr:1 row_mask:0xf bank_mask:0xf
	v_add_f32_dpp v178, v178, v162 row_shr:1 row_mask:0xf bank_mask:0xf
	v_add_f32_dpp v179, v179, v163 row_shr:1 row_mask:0xf bank_mask:0xf
	v_add_f32_dpp v176, v176, v160 row_shr:1 row_mask:0xf bank_mask:0xf
	v_add_f32_dpp v177, v177, v161 row_shr:1 row_mask:0xf bank_mask:0xf
	v_add_f32_dpp v178, v178, v162 row_shr:1 row_mask:0xf bank_mask:0xf
	v_add_f32_dpp v179, v179, v163 row_shr:1 row_mask:0xf bank_mask:0xf
	v_add_f32_dpp v176, v176, v160 row_shr:1 row_mask:0xf bank_mask:0xf
	v_add_f32_dpp v177, v177, v161 row_shr:1 row_mask:0xf bank_mask:0xf
	v_add_f32_dpp v178, v178, v162 row_shr:1 row_mask:0xf bank_mask:0xf
	v_add_f32_dpp v179, v179, v163 row_shr:1 row_mask:0xf bank_mask:0xf
	v_add_f32_dpp v176, v176, v160 row_shr:1 row_mask:0xf bank_mask:0xf
	v_add_f32_dpp v177, v177, v161 row_shr:1 row_mask:0xf bank_mask:0xf
	v_add_f32_dpp v178, v178, v162 row_shr:1 row_mask:0xf bank_mask:0xf
	v_add_f32_dpp v179, v179, v163 row_shr:1 row_mask:0xf bank_mask:0xf
	v_add_f32_dpp v176, v176, v160 row_shr:1 row_mask:0xf bank_mask:0xf
	v_add_f32_dpp v177, v177, v161 row_shr:1 row_mask:0xf bank_mask:0xf
	v_add_f32_dpp v178, v178, v162 row_shr:1 row_mask:0xf bank_mask:0xf
	v_add_f32_dpp v179, v179, v163 row_shr:1 row_mask:0xf bank_mask:0xf
	v_add_f32_dpp v176, v176, v160 row_shr:1 row_mask:0xf bank_mask:0xf
	v_add_f32_dpp v177, v177, v161 row_shr:1 row_mask:0xf bank_mask:0xf
	v_add_f32_dpp v178, v178, v162 row_shr:1 row_mask:0xf bank_mask:0xf
	v_add_f32_dpp v179, v179, v163 row_shr:1 row_mask:0xf bank_mask:0xf
	v_add_f32_e32 v227, v177, v176
	v_add_f32_e32 v229, v178, v179
	v_add_f32_e32 v212, v227, v229
	v_fmamk_f32 v213, v212, 0x3a000000, v232
	v_mul_f32_e32 v214, 0x4f800000, v213
	v_cmp_gt_f32_e32 vcc, s10, v213
	s_nop 1
	v_cndmask_b32_e32 v215, v213, v214, vcc
	v_sqrt_f32_e32 v216, v215
	s_nop 0
	v_add_u32_e32 v217, -1, v216
	v_add_u32_e32 v218, 1, v216
	v_fma_f32 v219, -v217, v216, v215
	v_fma_f32 v220, -v218, v216, v215
	v_cmp_ge_f32_e64 s[0:1], 0, v219
	s_nop 1
	v_cndmask_b32_e64 v221, v216, v217, s[0:1]
	v_cmp_lt_f32_e64 s[0:1], 0, v220
	s_nop 1
	v_cndmask_b32_e64 v221, v221, v218, s[0:1]
	v_mul_f32_e32 v222, 0x37800000, v221
	v_cndmask_b32_e32 v221, v221, v222, vcc
	v_cmp_class_f32_e32 vcc, v215, v233
	s_nop 1
	v_cndmask_b32_e32 v223, v221, v215, vcc
	v_div_scale_f32 v224, s[0:1], v223, v223, 1.0
	v_rcp_f32_e32 v225, v224
	v_div_scale_f32 v226, vcc, 1.0, v223, 1.0
	v_fma_f32 v227, -v224, v225, 1.0
	v_fmac_f32_e32 v225, v227, v225
	v_mul_f32_e32 v228, v226, v225
	v_fma_f32 v229, -v224, v228, v226
	v_fmac_f32_e32 v228, v229, v225
	v_fma_f32 v227, -v224, v228, v226
	v_div_fmas_f32 v230, v227, v225, v228
	v_div_fixup_f32 v231, v230, v223, 1.0
	s_nop 1
	v_readlane_b32 s52, v231, 7
	s_nop 1
	s_waitcnt vmcnt(58)
; __device__ __forceinline__ void phase_final(const Params& p) {
;     ...
;         for (int u = 0; u < UR; ++u) { const int row = row0 + u * NGW; const f32x4* xr = (const f32x4*)(p.out + (size_t)row * DM) + lane;
; #pragma unroll
;             for (int j = 0; j < 8; ++j) v[u][j] = xr[64 * j];
;             const f32x4* sp = (const f32x4*)(ssq + (size_t)row * 32); f32x4 s = sp[0];
; #pragma unroll
;             for (int i = 1; i < 8; ++i) s += sp[i];
;             rs[u] = 1.0f / sqrtf(((s[0] + s[1]) + (s[2] + s[3])) * (1.0f / DM) + 1e-6f); }
; #pragma unroll
;         for (int u = 0; u < UR; ++u) { f32x4* xr = (f32x4*)(p.out + (size_t)(row0 + u * NGW) * DM) + lane;
; #pragma unroll
;             for (int j = 0; j < 8; ++j) __builtin_nontemporal_store(v[u][j] * rs[u] * g4[j], xr + 64 * j); } }
	v_pk_mul_f32 v[196:197], v[32:33], s[52:53] op_sel_hi:[1,0]
	v_pk_mul_f32 v[198:199], v[34:35], s[52:53] op_sel_hi:[1,0]
	v_pk_mul_f32 v[196:197], v[0:1], v[196:197]
	v_pk_mul_f32 v[198:199], v[2:3], v[198:199]
	global_store_dwordx4 v241, v[196:199], s[36:37] nt
	s_waitcnt vmcnt(58)
	v_pk_mul_f32 v[200:201], v[36:37], s[52:53] op_sel_hi:[1,0]
	v_pk_mul_f32 v[202:203], v[38:39], s[52:53] op_sel_hi:[1,0]
	v_pk_mul_f32 v[200:201], v[4:5], v[200:201]
	v_pk_mul_f32 v[202:203], v[6:7], v[202:203]
	global_store_dwordx4 v241, v[200:203], s[36:37] offset:1024 nt
	s_waitcnt vmcnt(58)
	v_pk_mul_f32 v[204:205], v[40:41], s[52:53] op_sel_hi:[1,0]
	v_pk_mul_f32 v[206:207], v[42:43], s[52:53] op_sel_hi:[1,0]
	v_pk_mul_f32 v[204:205], v[8:9], v[204:205]
	v_pk_mul_f32 v[206:207], v[10:11], v[206:207]
	global_store_dwordx4 v241, v[204:207], s[36:37] offset:2048 nt
	s_waitcnt vmcnt(58)
	v_pk_mul_f32 v[208:209], v[44:45], s[52:53] op_sel_hi:[1,0]
	v_pk_mul_f32 v[210:211], v[46:47], s[52:53] op_sel_hi:[1,0]
	v_pk_mul_f32 v[208:209], v[12:13], v[208:209]
	v_pk_mul_f32 v[210:211], v[14:15], v[210:211]
	global_store_dwordx4 v241, v[208:211], s[36:37] offset:3072 nt
	s_waitcnt vmcnt(58)
	v_pk_mul_f32 v[196:197], v[48:49], s[52:53] op_sel_hi:[1,0]
	v_pk_mul_f32 v[198:199], v[50:51], s[52:53] op_sel_hi:[1,0]
	v_pk_mul_f32 v[196:197], v[16:17], v[196:197]
	v_pk_mul_f32 v[198:199], v[18:19], v[198:199]
	global_store_dwordx4 v242, v[196:199], s[36:37] nt
	s_waitcnt vmcnt(58)
	v_pk_mul_f32 v[200:201], v[52:53], s[52:53] op_sel_hi:[1,0]
	v_pk_mul_f32 v[202:203], v[54:55], s[52:53] op_sel_hi:[1,0]
	v_pk_mul_f32 v[200:201], v[20:21], v[200:201]
	v_pk_mul_f32 v[202:203], v[22:23], v[202:203]
	global_store_dwordx4 v242, v[200:203], s[36:37] offset:1024 nt
	s_waitcnt vmcnt(58)
	v_pk_mul_f32 v[204:205], v[56:57], s[52:53] op_sel_hi:[1,0]
	v_pk_mul_f32 v[206:207], v[58:59], s[52:53] op_sel_hi:[1,0]
	v_pk_mul_f32 v[204:205], v[24:25], v[204:205]
	v_pk_mul_f32 v[206:207], v[26:27], v[206:207]
	global_store_dwordx4 v242, v[204:207], s[36:37] offset:2048 nt
	s_waitcnt vmcnt(58)
	v_pk_mul_f32 v[208:209], v[60:61], s[52:53] op_sel_hi:[1,0]
	v_pk_mul_f32 v[210:211], v[62:63], s[52:53] op_sel_hi:[1,0]
	v_pk_mul_f32 v[208:209], v[28:29], v[208:209]
	v_pk_mul_f32 v[210:211], v[30:31], v[210:211]
	global_store_dwordx4 v242, v[208:211], s[36:37] offset:3072 nt
	s_lshl_b32 s8, s7, 13
	s_add_u32 s44, s26, s8
	s_addc_u32 s45, s27, 0
	s_lshl_b32 s8, s7, 7
	s_add_u32 s68, s2, s8
	s_addc_u32 s69, s3, 0
	s_add_u32 s7, s7, s6
	global_load_dwordx4 v[160:163], v243, s[68:69]
	s_waitcnt vmcnt(52)
	global_load_dwordx4 v[32:35], v241, s[44:45]
	global_load_dwordx4 v[36:39], v241, s[44:45] offset:1024
	global_load_dwordx4 v[40:43], v241, s[44:45] offset:2048
	global_load_dwordx4 v[44:47], v241, s[44:45] offset:3072
	global_load_dwordx4 v[48:51], v242, s[44:45]
	global_load_dwordx4 v[52:55], v242, s[44:45] offset:1024
	global_load_dwordx4 v[56:59], v242, s[44:45] offset:2048
	global_load_dwordx4 v[60:63], v242, s[44:45] offset:3072
	s_waitcnt vmcnt(59)
	v_mov_b32_e32 v180, v164
	v_mov_b32_e32 v181, v165
	v_mov_b32_e32 v182, v166
	v_mov_b32_e32 v183, v167
	v_add_f32_dpp v180, v180, v164 row_shr:1 row_mask:0xf bank_mask:0xf
	v_add_f32_dpp v181, v181, v165 row_shr:1 row_mask:0xf bank_mask:0xf
	v_add_f32_dpp v182, v182, v166 row_shr:1 row_mask:0xf bank_mask:0xf
	v_add_f32_dpp v183, v183, v167 row_shr:1 row_mask:0xf bank_mask:0xf
	v_add_f32_dpp v180, v180, v164 row_shr:1 row_mask:0xf bank_mask:0xf
	v_add_f32_dpp v181, v181, v165 row_shr:1 row_mask:0xf bank_mask:0xf
	v_add_f32_dpp v182, v182, v166 row_shr:1 row_mask:0xf bank_mask:0xf
	v_add_f32_dpp v183, v183, v167 row_shr:1 row_mask:0xf bank_mask:0xf
	v_add_f32_dpp v180, v180, v164 row_shr:1 row_mask:0xf bank_mask:0xf
	v_add_f32_dpp v181, v181, v165 row_shr:1 row_mask:0xf bank_mask:0xf
	v_add_f32_dpp v182, v182, v166 row_shr:1 row_mask:0xf bank_mask:0xf
	v_add_f32_dpp v183, v183, v167 row_shr:1 row_mask:0xf bank_mask:0xf
	v_add_f32_dpp v180, v180, v164 row_shr:1 row_mask:0xf bank_mask:0xf
	v_add_f32_dpp v181, v181, v165 row_shr:1 row_mask:0xf bank_mask:0xf
	v_add_f32_dpp v182, v182, v166 row_shr:1 row_mask:0xf bank_mask:0xf
	v_add_f32_dpp v183, v183, v167 row_shr:1 row_mask:0xf bank_mask:0xf
	v_add_f32_dpp v180, v180, v164 row_shr:1 row_mask:0xf bank_mask:0xf
	v_add_f32_dpp v181, v181, v165 row_shr:1 row_mask:0xf bank_mask:0xf
	v_add_f32_dpp v182, v182, v166 row_shr:1 row_mask:0xf bank_mask:0xf
	v_add_f32_dpp v183, v183, v167 row_shr:1 row_mask:0xf bank_mask:0xf
	v_add_f32_dpp v180, v180, v164 row_shr:1 row_mask:0xf bank_mask:0xf
	v_add_f32_dpp v181, v181, v165 row_shr:1 row_mask:0xf bank_mask:0xf
	v_add_f32_dpp v182, v182, v166 row_shr:1 row_mask:0xf bank_mask:0xf
	v_add_f32_dpp v183, v183, v167 row_shr:1 row_mask:0xf bank_mask:0xf
	v_add_f32_dpp v180, v180, v164 row_shr:1 row_mask:0xf bank_mask:0xf
	v_add_f32_dpp v181, v181, v165 row_shr:1 row_mask:0xf bank_mask:0xf
	v_add_f32_dpp v182, v182, v166 row_shr:1 row_mask:0xf bank_mask:0xf
	v_add_f32_dpp v183, v183, v167 row_shr:1 row_mask:0xf bank_mask:0xf
	v_add_f32_e32 v227, v181, v180
	v_add_f32_e32 v229, v182, v183
	v_add_f32_e32 v212, v227, v229
	v_fmamk_f32 v213, v212, 0x3a000000, v232
	v_mul_f32_e32 v214, 0x4f800000, v213
	v_cmp_gt_f32_e32 vcc, s10, v213
	s_nop 1
	v_cndmask_b32_e32 v215, v213, v214, vcc
	v_sqrt_f32_e32 v216, v215
	s_nop 0
	v_add_u32_e32 v217, -1, v216
	v_add_u32_e32 v218, 1, v216
	v_fma_f32 v219, -v217, v216, v215
	v_fma_f32 v220, -v218, v216, v215
	v_cmp_ge_f32_e64 s[0:1], 0, v219
	s_nop 1
	v_cndmask_b32_e64 v221, v216, v217, s[0:1]
	v_cmp_lt_f32_e64 s[0:1], 0, v220
	s_nop 1
	v_cndmask_b32_e64 v221, v221, v218, s[0:1]
	v_mul_f32_e32 v222, 0x37800000, v221
	v_cndmask_b32_e32 v221, v221, v222, vcc
	v_cmp_class_f32_e32 vcc, v215, v233
	s_nop 1
	v_cndmask_b32_e32 v223, v221, v215, vcc
	v_div_scale_f32 v224, s[0:1], v223, v223, 1.0
	v_rcp_f32_e32 v225, v224
	v_div_scale_f32 v226, vcc, 1.0, v223, 1.0
	v_fma_f32 v227, -v224, v225, 1.0
	v_fmac_f32_e32 v225, v227, v225
	v_mul_f32_e32 v228, v226, v225
	v_fma_f32 v229, -v224, v228, v226
	v_fmac_f32_e32 v228, v229, v225
	v_fma_f32 v227, -v224, v228, v226
	v_div_fmas_f32 v230, v227, v225, v228
	v_div_fixup_f32 v231, v230, v223, 1.0
	s_nop 1
	v_readlane_b32 s54, v231, 7
	s_nop 1
	s_waitcnt vmcnt(58)
; __device__ __forceinline__ void phase_final(const Params& p) {
;     ...
;         for (int u = 0; u < UR; ++u) { const int row = row0 + u * NGW; const f32x4* xr = (const f32x4*)(p.out + (size_t)row * DM) + lane;
; #pragma unroll
;             for (int j = 0; j < 8; ++j) v[u][j] = xr[64 * j];
;             const f32x4* sp = (const f32x4*)(ssq + (size_t)row * 32); f32x4 s = sp[0];
; #pragma unroll
;             for (int i = 1; i < 8; ++i) s += sp[i];
;             rs[u] = 1.0f / sqrtf(((s[0] + s[1]) + (s[2] + s[3])) * (1.0f / DM) + 1e-6f); }
; #pragma unroll
;         for (int u = 0; u < UR; ++u) { f32x4* xr = (f32x4*)(p.out + (size_t)(row0 + u * NGW) * DM) + lane;
; #pragma unroll
;             for (int j = 0; j < 8; ++j) __builtin_nontemporal_store(v[u][j] * rs[u] * g4[j], xr + 64 * j); } }
	v_pk_mul_f32 v[196:197], v[64:65], s[54:55] op_sel_hi:[1,0]
	v_pk_mul_f32 v[198:199], v[66:67], s[54:55] op_sel_hi:[1,0]
	v_pk_mul_f32 v[196:197], v[0:1], v[196:197]
	v_pk_mul_f32 v[198:199], v[2:3], v[198:199]
	global_store_dwordx4 v241, v[196:199], s[38:39] nt
	s_waitcnt vmcnt(58)
	v_pk_mul_f32 v[200:201], v[68:69], s[54:55] op_sel_hi:[1,0]
	v_pk_mul_f32 v[202:203], v[70:71], s[54:55] op_sel_hi:[1,0]
	v_pk_mul_f32 v[200:201], v[4:5], v[200:201]
	v_pk_mul_f32 v[202:203], v[6:7], v[202:203]
	global_store_dwordx4 v241, v[200:203], s[38:39] offset:1024 nt
	s_waitcnt vmcnt(58)
	v_pk_mul_f32 v[204:205], v[72:73], s[54:55] op_sel_hi:[1,0]
	v_pk_mul_f32 v[206:207], v[74:75], s[54:55] op_sel_hi:[1,0]
	v_pk_mul_f32 v[204:205], v[8:9], v[204:205]
	v_pk_mul_f32 v[206:207], v[10:11], v[206:207]
	global_store_dwordx4 v241, v[204:207], s[38:39] offset:2048 nt
	s_waitcnt vmcnt(58)
	v_pk_mul_f32 v[208:209], v[76:77], s[54:55] op_sel_hi:[1,0]
	v_pk_mul_f32 v[210:211], v[78:79], s[54:55] op_sel_hi:[1,0]
	v_pk_mul_f32 v[208:209], v[12:13], v[208:209]
	v_pk_mul_f32 v[210:211], v[14:15], v[210:211]
	global_store_dwordx4 v241, v[208:211], s[38:39] offset:3072 nt
	s_waitcnt vmcnt(58)
	v_pk_mul_f32 v[196:197], v[80:81], s[54:55] op_sel_hi:[1,0]
	v_pk_mul_f32 v[198:199], v[82:83], s[54:55] op_sel_hi:[1,0]
	v_pk_mul_f32 v[196:197], v[16:17], v[196:197]
	v_pk_mul_f32 v[198:199], v[18:19], v[198:199]
	global_store_dwordx4 v242, v[196:199], s[38:39] nt
	s_waitcnt vmcnt(58)
	v_pk_mul_f32 v[200:201], v[84:85], s[54:55] op_sel_hi:[1,0]
	v_pk_mul_f32 v[202:203], v[86:87], s[54:55] op_sel_hi:[1,0]
	v_pk_mul_f32 v[200:201], v[20:21], v[200:201]
	v_pk_mul_f32 v[202:203], v[22:23], v[202:203]
	global_store_dwordx4 v242, v[200:203], s[38:39] offset:1024 nt
	s_waitcnt vmcnt(58)
	v_pk_mul_f32 v[204:205], v[88:89], s[54:55] op_sel_hi:[1,0]
	v_pk_mul_f32 v[206:207], v[90:91], s[54:55] op_sel_hi:[1,0]
	v_pk_mul_f32 v[204:205], v[24:25], v[204:205]
	v_pk_mul_f32 v[206:207], v[26:27], v[206:207]
	global_store_dwordx4 v242, v[204:207], s[38:39] offset:2048 nt
	s_waitcnt vmcnt(58)
	v_pk_mul_f32 v[208:209], v[92:93], s[54:55] op_sel_hi:[1,0]
	v_pk_mul_f32 v[210:211], v[94:95], s[54:55] op_sel_hi:[1,0]
	v_pk_mul_f32 v[208:209], v[28:29], v[208:209]
	v_pk_mul_f32 v[210:211], v[30:31], v[210:211]
	global_store_dwordx4 v242, v[208:211], s[38:39] offset:3072 nt
	s_lshl_b32 s8, s7, 13
	s_add_u32 s46, s26, s8
	s_addc_u32 s47, s27, 0
	s_lshl_b32 s8, s7, 7
	s_add_u32 s70, s2, s8
	s_addc_u32 s71, s3, 0
	s_add_u32 s7, s7, s6
	global_load_dwordx4 v[164:167], v243, s[70:71]
	s_waitcnt vmcnt(52)
	global_load_dwordx4 v[64:67], v241, s[46:47]
	global_load_dwordx4 v[68:71], v241, s[46:47] offset:1024
	global_load_dwordx4 v[72:75], v241, s[46:47] offset:2048
	global_load_dwordx4 v[76:79], v241, s[46:47] offset:3072
	global_load_dwordx4 v[80:83], v242, s[46:47]
	global_load_dwordx4 v[84:87], v242, s[46:47] offset:1024
	global_load_dwordx4 v[88:91], v242, s[46:47] offset:2048
	global_load_dwordx4 v[92:95], v242, s[46:47] offset:3072
	s_waitcnt vmcnt(59)
	v_mov_b32_e32 v184, v168
	v_mov_b32_e32 v185, v169
	v_mov_b32_e32 v186, v170
	v_mov_b32_e32 v187, v171
	v_add_f32_dpp v184, v184, v168 row_shr:1 row_mask:0xf bank_mask:0xf
	v_add_f32_dpp v185, v185, v169 row_shr:1 row_mask:0xf bank_mask:0xf
	v_add_f32_dpp v186, v186, v170 row_shr:1 row_mask:0xf bank_mask:0xf
	v_add_f32_dpp v187, v187, v171 row_shr:1 row_mask:0xf bank_mask:0xf
	v_add_f32_dpp v184, v184, v168 row_shr:1 row_mask:0xf bank_mask:0xf
	v_add_f32_dpp v185, v185, v169 row_shr:1 row_mask:0xf bank_mask:0xf
	v_add_f32_dpp v186, v186, v170 row_shr:1 row_mask:0xf bank_mask:0xf
	v_add_f32_dpp v187, v187, v171 row_shr:1 row_mask:0xf bank_mask:0xf
	v_add_f32_dpp v184, v184, v168 row_shr:1 row_mask:0xf bank_mask:0xf
	v_add_f32_dpp v185, v185, v169 row_shr:1 row_mask:0xf bank_mask:0xf
	v_add_f32_dpp v186, v186, v170 row_shr:1 row_mask:0xf bank_mask:0xf
	v_add_f32_dpp v187, v187, v171 row_shr:1 row_mask:0xf bank_mask:0xf
	v_add_f32_dpp v184, v184, v168 row_shr:1 row_mask:0xf bank_mask:0xf
	v_add_f32_dpp v185, v185, v169 row_shr:1 row_mask:0xf bank_mask:0xf
	v_add_f32_dpp v186, v186, v170 row_shr:1 row_mask:0xf bank_mask:0xf
	v_add_f32_dpp v187, v187, v171 row_shr:1 row_mask:0xf bank_mask:0xf
	v_add_f32_dpp v184, v184, v168 row_shr:1 row_mask:0xf bank_mask:0xf
	v_add_f32_dpp v185, v185, v169 row_shr:1 row_mask:0xf bank_mask:0xf
	v_add_f32_dpp v186, v186, v170 row_shr:1 row_mask:0xf bank_mask:0xf
	v_add_f32_dpp v187, v187, v171 row_shr:1 row_mask:0xf bank_mask:0xf
	v_add_f32_dpp v184, v184, v168 row_shr:1 row_mask:0xf bank_mask:0xf
	v_add_f32_dpp v185, v185, v169 row_shr:1 row_mask:0xf bank_mask:0xf
	v_add_f32_dpp v186, v186, v170 row_shr:1 row_mask:0xf bank_mask:0xf
	v_add_f32_dpp v187, v187, v171 row_shr:1 row_mask:0xf bank_mask:0xf
	v_add_f32_dpp v184, v184, v168 row_shr:1 row_mask:0xf bank_mask:0xf
	v_add_f32_dpp v185, v185, v169 row_shr:1 row_mask:0xf bank_mask:0xf
	v_add_f32_dpp v186, v186, v170 row_shr:1 row_mask:0xf bank_mask:0xf
	v_add_f32_dpp v187, v187, v171 row_shr:1 row_mask:0xf bank_mask:0xf
	v_add_f32_e32 v227, v185, v184
	v_add_f32_e32 v229, v186, v187
	v_add_f32_e32 v212, v227, v229
	v_fmamk_f32 v213, v212, 0x3a000000, v232
	v_mul_f32_e32 v214, 0x4f800000, v213
	v_cmp_gt_f32_e32 vcc, s10, v213
	s_nop 1
	v_cndmask_b32_e32 v215, v213, v214, vcc
	v_sqrt_f32_e32 v216, v215
	s_nop 0
	v_add_u32_e32 v217, -1, v216
	v_add_u32_e32 v218, 1, v216
	v_fma_f32 v219, -v217, v216, v215
	v_fma_f32 v220, -v218, v216, v215
	v_cmp_ge_f32_e64 s[0:1], 0, v219
	s_nop 1
	v_cndmask_b32_e64 v221, v216, v217, s[0:1]
	v_cmp_lt_f32_e64 s[0:1], 0, v220
	s_nop 1
	v_cndmask_b32_e64 v221, v221, v218, s[0:1]
	v_mul_f32_e32 v222, 0x37800000, v221
	v_cndmask_b32_e32 v221, v221, v222, vcc
	v_cmp_class_f32_e32 vcc, v215, v233
	s_nop 1
	v_cndmask_b32_e32 v223, v221, v215, vcc
	v_div_scale_f32 v224, s[0:1], v223, v223, 1.0
	v_rcp_f32_e32 v225, v224
	v_div_scale_f32 v226, vcc, 1.0, v223, 1.0
	v_fma_f32 v227, -v224, v225, 1.0
	v_fmac_f32_e32 v225, v227, v225
	v_mul_f32_e32 v228, v226, v225
	v_fma_f32 v229, -v224, v228, v226
	v_fmac_f32_e32 v228, v229, v225
	v_fma_f32 v227, -v224, v228, v226
	v_div_fmas_f32 v230, v227, v225, v228
	v_div_fixup_f32 v231, v230, v223, 1.0
	s_nop 1
	v_readlane_b32 s56, v231, 7
	s_nop 1
	s_waitcnt vmcnt(58)
; __device__ __forceinline__ void phase_final(const Params& p) {
;     ...
;         for (int u = 0; u < UR; ++u) { const int row = row0 + u * NGW; const f32x4* xr = (const f32x4*)(p.out + (size_t)row * DM) + lane;
; #pragma unroll
;             for (int j = 0; j < 8; ++j) v[u][j] = xr[64 * j];
;             const f32x4* sp = (const f32x4*)(ssq + (size_t)row * 32); f32x4 s = sp[0];
; #pragma unroll
;             for (int i = 1; i < 8; ++i) s += sp[i];
;             rs[u] = 1.0f / sqrtf(((s[0] + s[1]) + (s[2] + s[3])) * (1.0f / DM) + 1e-6f); }
; #pragma unroll
;         for (int u = 0; u < UR; ++u) { f32x4* xr = (f32x4*)(p.out + (size_t)(row0 + u * NGW) * DM) + lane;
; #pragma unroll
;             for (int j = 0; j < 8; ++j) __builtin_nontemporal_store(v[u][j] * rs[u] * g4[j], xr + 64 * j); } }
	v_pk_mul_f32 v[196:197], v[96:97], s[56:57] op_sel_hi:[1,0]
	v_pk_mul_f32 v[198:199], v[98:99], s[56:57] op_sel_hi:[1,0]
	v_pk_mul_f32 v[196:197], v[0:1], v[196:197]
	v_pk_mul_f32 v[198:199], v[2:3], v[198:199]
	global_store_dwordx4 v241, v[196:199], s[40:41] nt
	s_waitcnt vmcnt(58)
	v_pk_mul_f32 v[200:201], v[100:101], s[56:57] op_sel_hi:[1,0]
	v_pk_mul_f32 v[202:203], v[102:103], s[56:57] op_sel_hi:[1,0]
	v_pk_mul_f32 v[200:201], v[4:5], v[200:201]
	v_pk_mul_f32 v[202:203], v[6:7], v[202:203]
	global_store_dwordx4 v241, v[200:203], s[40:41] offset:1024 nt
	s_waitcnt vmcnt(58)
	v_pk_mul_f32 v[204:205], v[104:105], s[56:57] op_sel_hi:[1,0]
	v_pk_mul_f32 v[206:207], v[106:107], s[56:57] op_sel_hi:[1,0]
	v_pk_mul_f32 v[204:205], v[8:9], v[204:205]
	v_pk_mul_f32 v[206:207], v[10:11], v[206:207]
	global_store_dwordx4 v241, v[204:207], s[40:41] offset:2048 nt
	s_waitcnt vmcnt(58)
	v_pk_mul_f32 v[208:209], v[108:109], s[56:57] op_sel_hi:[1,0]
	v_pk_mul_f32 v[210:211], v[110:111], s[56:57] op_sel_hi:[1,0]
	v_pk_mul_f32 v[208:209], v[12:13], v[208:209]
	v_pk_mul_f32 v[210:211], v[14:15], v[210:211]
	global_store_dwordx4 v241, v[208:211], s[40:41] offset:3072 nt
	s_waitcnt vmcnt(58)
	v_pk_mul_f32 v[196:197], v[112:113], s[56:57] op_sel_hi:[1,0]
	v_pk_mul_f32 v[198:199], v[114:115], s[56:57] op_sel_hi:[1,0]
	v_pk_mul_f32 v[196:197], v[16:17], v[196:197]
	v_pk_mul_f32 v[198:199], v[18:19], v[198:199]
	global_store_dwordx4 v242, v[196:199], s[40:41] nt
	s_waitcnt vmcnt(58)
	v_pk_mul_f32 v[200:201], v[116:117], s[56:57] op_sel_hi:[1,0]
	v_pk_mul_f32 v[202:203], v[118:119], s[56:57] op_sel_hi:[1,0]
	v_pk_mul_f32 v[200:201], v[20:21], v[200:201]
	v_pk_mul_f32 v[202:203], v[22:23], v[202:203]
	global_store_dwordx4 v242, v[200:203], s[40:41] offset:1024 nt
	s_waitcnt vmcnt(58)
	v_pk_mul_f32 v[204:205], v[120:121], s[56:57] op_sel_hi:[1,0]
	v_pk_mul_f32 v[206:207], v[122:123], s[56:57] op_sel_hi:[1,0]
	v_pk_mul_f32 v[204:205], v[24:25], v[204:205]
	v_pk_mul_f32 v[206:207], v[26:27], v[206:207]
	global_store_dwordx4 v242, v[204:207], s[40:41] offset:2048 nt
	s_waitcnt vmcnt(58)
	v_pk_mul_f32 v[208:209], v[124:125], s[56:57] op_sel_hi:[1,0]
	v_pk_mul_f32 v[210:211], v[126:127], s[56:57] op_sel_hi:[1,0]
	v_pk_mul_f32 v[208:209], v[28:29], v[208:209]
	v_pk_mul_f32 v[210:211], v[30:31], v[210:211]
	global_store_dwordx4 v242, v[208:211], s[40:41] offset:3072 nt
	s_lshl_b32 s8, s7, 13
	s_add_u32 s48, s26, s8
	s_addc_u32 s49, s27, 0
	s_lshl_b32 s8, s7, 7
	s_add_u32 s72, s2, s8
	s_addc_u32 s73, s3, 0
	s_add_u32 s7, s7, s6
	global_load_dwordx4 v[168:171], v243, s[72:73]
	s_waitcnt vmcnt(52)
	global_load_dwordx4 v[96:99], v241, s[48:49]
	global_load_dwordx4 v[100:103], v241, s[48:49] offset:1024
	global_load_dwordx4 v[104:107], v241, s[48:49] offset:2048
	global_load_dwordx4 v[108:111], v241, s[48:49] offset:3072
	global_load_dwordx4 v[112:115], v242, s[48:49]
	global_load_dwordx4 v[116:119], v242, s[48:49] offset:1024
	global_load_dwordx4 v[120:123], v242, s[48:49] offset:2048
	global_load_dwordx4 v[124:127], v242, s[48:49] offset:3072
	s_waitcnt vmcnt(59)
	v_mov_b32_e32 v188, v172
	v_mov_b32_e32 v189, v173
	v_mov_b32_e32 v190, v174
	v_mov_b32_e32 v191, v175
	v_add_f32_dpp v188, v188, v172 row_shr:1 row_mask:0xf bank_mask:0xf
	v_add_f32_dpp v189, v189, v173 row_shr:1 row_mask:0xf bank_mask:0xf
	v_add_f32_dpp v190, v190, v174 row_shr:1 row_mask:0xf bank_mask:0xf
	v_add_f32_dpp v191, v191, v175 row_shr:1 row_mask:0xf bank_mask:0xf
	v_add_f32_dpp v188, v188, v172 row_shr:1 row_mask:0xf bank_mask:0xf
	v_add_f32_dpp v189, v189, v173 row_shr:1 row_mask:0xf bank_mask:0xf
	v_add_f32_dpp v190, v190, v174 row_shr:1 row_mask:0xf bank_mask:0xf
	v_add_f32_dpp v191, v191, v175 row_shr:1 row_mask:0xf bank_mask:0xf
	v_add_f32_dpp v188, v188, v172 row_shr:1 row_mask:0xf bank_mask:0xf
	v_add_f32_dpp v189, v189, v173 row_shr:1 row_mask:0xf bank_mask:0xf
	v_add_f32_dpp v190, v190, v174 row_shr:1 row_mask:0xf bank_mask:0xf
	v_add_f32_dpp v191, v191, v175 row_shr:1 row_mask:0xf bank_mask:0xf
	v_add_f32_dpp v188, v188, v172 row_shr:1 row_mask:0xf bank_mask:0xf
	v_add_f32_dpp v189, v189, v173 row_shr:1 row_mask:0xf bank_mask:0xf
	v_add_f32_dpp v190, v190, v174 row_shr:1 row_mask:0xf bank_mask:0xf
	v_add_f32_dpp v191, v191, v175 row_shr:1 row_mask:0xf bank_mask:0xf
	v_add_f32_dpp v188, v188, v172 row_shr:1 row_mask:0xf bank_mask:0xf
	v_add_f32_dpp v189, v189, v173 row_shr:1 row_mask:0xf bank_mask:0xf
	v_add_f32_dpp v190, v190, v174 row_shr:1 row_mask:0xf bank_mask:0xf
	v_add_f32_dpp v191, v191, v175 row_shr:1 row_mask:0xf bank_mask:0xf
	v_add_f32_dpp v188, v188, v172 row_shr:1 row_mask:0xf bank_mask:0xf
	v_add_f32_dpp v189, v189, v173 row_shr:1 row_mask:0xf bank_mask:0xf
	v_add_f32_dpp v190, v190, v174 row_shr:1 row_mask:0xf bank_mask:0xf
	v_add_f32_dpp v191, v191, v175 row_shr:1 row_mask:0xf bank_mask:0xf
	v_add_f32_dpp v188, v188, v172 row_shr:1 row_mask:0xf bank_mask:0xf
	v_add_f32_dpp v189, v189, v173 row_shr:1 row_mask:0xf bank_mask:0xf
	v_add_f32_dpp v190, v190, v174 row_shr:1 row_mask:0xf bank_mask:0xf
	v_add_f32_dpp v191, v191, v175 row_shr:1 row_mask:0xf bank_mask:0xf
	v_add_f32_e32 v227, v189, v188
	v_add_f32_e32 v229, v190, v191
	v_add_f32_e32 v212, v227, v229
	v_fmamk_f32 v213, v212, 0x3a000000, v232
	v_mul_f32_e32 v214, 0x4f800000, v213
	v_cmp_gt_f32_e32 vcc, s10, v213
	s_nop 1
	v_cndmask_b32_e32 v215, v213, v214, vcc
	v_sqrt_f32_e32 v216, v215
	s_nop 0
	v_add_u32_e32 v217, -1, v216
	v_add_u32_e32 v218, 1, v216
	v_fma_f32 v219, -v217, v216, v215
	v_fma_f32 v220, -v218, v216, v215
	v_cmp_ge_f32_e64 s[0:1], 0, v219
	s_nop 1
	v_cndmask_b32_e64 v221, v216, v217, s[0:1]
	v_cmp_lt_f32_e64 s[0:1], 0, v220
	s_nop 1
	v_cndmask_b32_e64 v221, v221, v218, s[0:1]
	v_mul_f32_e32 v222, 0x37800000, v221
	v_cndmask_b32_e32 v221, v221, v222, vcc
	v_cmp_class_f32_e32 vcc, v215, v233
	s_nop 1
	v_cndmask_b32_e32 v223, v221, v215, vcc
	v_div_scale_f32 v224, s[0:1], v223, v223, 1.0
	v_rcp_f32_e32 v225, v224
	v_div_scale_f32 v226, vcc, 1.0, v223, 1.0
	v_fma_f32 v227, -v224, v225, 1.0
	v_fmac_f32_e32 v225, v227, v225
	v_mul_f32_e32 v228, v226, v225
	v_fma_f32 v229, -v224, v228, v226
	v_fmac_f32_e32 v228, v229, v225
	v_fma_f32 v227, -v224, v228, v226
	v_div_fmas_f32 v230, v227, v225, v228
	v_div_fixup_f32 v231, v230, v223, 1.0
	s_nop 1
	v_readlane_b32 s58, v231, 7
	s_nop 1
	s_waitcnt vmcnt(58)
; __device__ __forceinline__ void phase_final(const Params& p) {
;     ...
;         for (int u = 0; u < UR; ++u) { const int row = row0 + u * NGW; const f32x4* xr = (const f32x4*)(p.out + (size_t)row * DM) + lane;
; #pragma unroll
;             for (int j = 0; j < 8; ++j) v[u][j] = xr[64 * j];
;             const f32x4* sp = (const f32x4*)(ssq + (size_t)row * 32); f32x4 s = sp[0];
; #pragma unroll
;             for (int i = 1; i < 8; ++i) s += sp[i];
;             rs[u] = 1.0f / sqrtf(((s[0] + s[1]) + (s[2] + s[3])) * (1.0f / DM) + 1e-6f); }
; #pragma unroll
;         for (int u = 0; u < UR; ++u) { f32x4* xr = (f32x4*)(p.out + (size_t)(row0 + u * NGW) * DM) + lane;
; #pragma unroll
;             for (int j = 0; j < 8; ++j) __builtin_nontemporal_store(v[u][j] * rs[u] * g4[j], xr + 64 * j); } }
	v_pk_mul_f32 v[196:197], v[128:129], s[58:59] op_sel_hi:[1,0]
	v_pk_mul_f32 v[198:199], v[130:131], s[58:59] op_sel_hi:[1,0]
	v_pk_mul_f32 v[196:197], v[0:1], v[196:197]
	v_pk_mul_f32 v[198:199], v[2:3], v[198:199]
	global_store_dwordx4 v241, v[196:199], s[42:43] nt
	s_waitcnt vmcnt(58)
	v_pk_mul_f32 v[200:201], v[132:133], s[58:59] op_sel_hi:[1,0]
	v_pk_mul_f32 v[202:203], v[134:135], s[58:59] op_sel_hi:[1,0]
	v_pk_mul_f32 v[200:201], v[4:5], v[200:201]
	v_pk_mul_f32 v[202:203], v[6:7], v[202:203]
	global_store_dwordx4 v241, v[200:203], s[42:43] offset:1024 nt
	s_waitcnt vmcnt(58)
	v_pk_mul_f32 v[204:205], v[136:137], s[58:59] op_sel_hi:[1,0]
	v_pk_mul_f32 v[206:207], v[138:139], s[58:59] op_sel_hi:[1,0]
	v_pk_mul_f32 v[204:205], v[8:9], v[204:205]
	v_pk_mul_f32 v[206:207], v[10:11], v[206:207]
	global_store_dwordx4 v241, v[204:207], s[42:43] offset:2048 nt
	s_waitcnt vmcnt(58)
	v_pk_mul_f32 v[208:209], v[140:141], s[58:59] op_sel_hi:[1,0]
	v_pk_mul_f32 v[210:211], v[142:143], s[58:59] op_sel_hi:[1,0]
	v_pk_mul_f32 v[208:209], v[12:13], v[208:209]
	v_pk_mul_f32 v[210:211], v[14:15], v[210:211]
	global_store_dwordx4 v241, v[208:211], s[42:43] offset:3072 nt
	s_waitcnt vmcnt(58)
	v_pk_mul_f32 v[196:197], v[144:145], s[58:59] op_sel_hi:[1,0]
	v_pk_mul_f32 v[198:199], v[146:147], s[58:59] op_sel_hi:[1,0]
	v_pk_mul_f32 v[196:197], v[16:17], v[196:197]
	v_pk_mul_f32 v[198:199], v[18:19], v[198:199]
	global_store_dwordx4 v242, v[196:199], s[42:43] nt
	s_waitcnt vmcnt(58)
	v_pk_mul_f32 v[200:201], v[148:149], s[58:59] op_sel_hi:[1,0]
	v_pk_mul_f32 v[202:203], v[150:151], s[58:59] op_sel_hi:[1,0]
	v_pk_mul_f32 v[200:201], v[20:21], v[200:201]
	v_pk_mul_f32 v[202:203], v[22:23], v[202:203]
	global_store_dwordx4 v242, v[200:203], s[42:43] offset:1024 nt
	s_waitcnt vmcnt(58)
	v_pk_mul_f32 v[204:205], v[152:153], s[58:59] op_sel_hi:[1,0]
	v_pk_mul_f32 v[206:207], v[154:155], s[58:59] op_sel_hi:[1,0]
	v_pk_mul_f32 v[204:205], v[24:25], v[204:205]
	v_pk_mul_f32 v[206:207], v[26:27], v[206:207]
	global_store_dwordx4 v242, v[204:207], s[42:43] offset:2048 nt
	s_waitcnt vmcnt(58)
	v_pk_mul_f32 v[208:209], v[156:157], s[58:59] op_sel_hi:[1,0]
	v_pk_mul_f32 v[210:211], v[158:159], s[58:59] op_sel_hi:[1,0]
	v_pk_mul_f32 v[208:209], v[28:29], v[208:209]
	v_pk_mul_f32 v[210:211], v[30:31], v[210:211]
	global_store_dwordx4 v242, v[208:211], s[42:43] offset:3072 nt
	s_lshl_b32 s8, s7, 13
	s_add_u32 s50, s26, s8
	s_addc_u32 s51, s27, 0
	s_lshl_b32 s8, s7, 7
	s_add_u32 s74, s2, s8
	s_addc_u32 s75, s3, 0
	s_add_u32 s7, s7, s6
	global_load_dwordx4 v[172:175], v243, s[74:75]
	s_waitcnt vmcnt(52)
	global_load_dwordx4 v[128:131], v241, s[50:51]
	global_load_dwordx4 v[132:135], v241, s[50:51] offset:1024
	global_load_dwordx4 v[136:139], v241, s[50:51] offset:2048
	global_load_dwordx4 v[140:143], v241, s[50:51] offset:3072
	global_load_dwordx4 v[144:147], v242, s[50:51]
	global_load_dwordx4 v[148:151], v242, s[50:51] offset:1024
	global_load_dwordx4 v[152:155], v242, s[50:51] offset:2048
	global_load_dwordx4 v[156:159], v242, s[50:51] offset:3072
	s_waitcnt vmcnt(59)
	v_mov_b32_e32 v176, v160
	v_mov_b32_e32 v177, v161
	v_mov_b32_e32 v178, v162
	v_mov_b32_e32 v179, v163
	v_add_f32_dpp v176, v176, v160 row_shr:1 row_mask:0xf bank_mask:0xf
	v_add_f32_dpp v177, v177, v161 row_shr:1 row_mask:0xf bank_mask:0xf
	v_add_f32_dpp v178, v178, v162 row_shr:1 row_mask:0xf bank_mask:0xf
	v_add_f32_dpp v179, v179, v163 row_shr:1 row_mask:0xf bank_mask:0xf
	v_add_f32_dpp v176, v176, v160 row_shr:1 row_mask:0xf bank_mask:0xf
	v_add_f32_dpp v177, v177, v161 row_shr:1 row_mask:0xf bank_mask:0xf
	v_add_f32_dpp v178, v178, v162 row_shr:1 row_mask:0xf bank_mask:0xf
	v_add_f32_dpp v179, v179, v163 row_shr:1 row_mask:0xf bank_mask:0xf
	v_add_f32_dpp v176, v176, v160 row_shr:1 row_mask:0xf bank_mask:0xf
	v_add_f32_dpp v177, v177, v161 row_shr:1 row_mask:0xf bank_mask:0xf
	v_add_f32_dpp v178, v178, v162 row_shr:1 row_mask:0xf bank_mask:0xf
	v_add_f32_dpp v179, v179, v163 row_shr:1 row_mask:0xf bank_mask:0xf
	v_add_f32_dpp v176, v176, v160 row_shr:1 row_mask:0xf bank_mask:0xf
	v_add_f32_dpp v177, v177, v161 row_shr:1 row_mask:0xf bank_mask:0xf
	v_add_f32_dpp v178, v178, v162 row_shr:1 row_mask:0xf bank_mask:0xf
	v_add_f32_dpp v179, v179, v163 row_shr:1 row_mask:0xf bank_mask:0xf
	v_add_f32_dpp v176, v176, v160 row_shr:1 row_mask:0xf bank_mask:0xf
	v_add_f32_dpp v177, v177, v161 row_shr:1 row_mask:0xf bank_mask:0xf
	v_add_f32_dpp v178, v178, v162 row_shr:1 row_mask:0xf bank_mask:0xf
	v_add_f32_dpp v179, v179, v163 row_shr:1 row_mask:0xf bank_mask:0xf
	v_add_f32_dpp v176, v176, v160 row_shr:1 row_mask:0xf bank_mask:0xf
	v_add_f32_dpp v177, v177, v161 row_shr:1 row_mask:0xf bank_mask:0xf
	v_add_f32_dpp v178, v178, v162 row_shr:1 row_mask:0xf bank_mask:0xf
	v_add_f32_dpp v179, v179, v163 row_shr:1 row_mask:0xf bank_mask:0xf
	v_add_f32_dpp v176, v176, v160 row_shr:1 row_mask:0xf bank_mask:0xf
	v_add_f32_dpp v177, v177, v161 row_shr:1 row_mask:0xf bank_mask:0xf
	v_add_f32_dpp v178, v178, v162 row_shr:1 row_mask:0xf bank_mask:0xf
	v_add_f32_dpp v179, v179, v163 row_shr:1 row_mask:0xf bank_mask:0xf
	v_add_f32_e32 v227, v177, v176
	v_add_f32_e32 v229, v178, v179
	v_add_f32_e32 v212, v227, v229
	v_fmamk_f32 v213, v212, 0x3a000000, v232
	v_mul_f32_e32 v214, 0x4f800000, v213
	v_cmp_gt_f32_e32 vcc, s10, v213
	s_nop 1
	v_cndmask_b32_e32 v215, v213, v214, vcc
	v_sqrt_f32_e32 v216, v215
	s_nop 0
	v_add_u32_e32 v217, -1, v216
	v_add_u32_e32 v218, 1, v216
	v_fma_f32 v219, -v217, v216, v215
	v_fma_f32 v220, -v218, v216, v215
	v_cmp_ge_f32_e64 s[0:1], 0, v219
	s_nop 1
	v_cndmask_b32_e64 v221, v216, v217, s[0:1]
	v_cmp_lt_f32_e64 s[0:1], 0, v220
	s_nop 1
	v_cndmask_b32_e64 v221, v221, v218, s[0:1]
	v_mul_f32_e32 v222, 0x37800000, v221
	v_cndmask_b32_e32 v221, v221, v222, vcc
	v_cmp_class_f32_e32 vcc, v215, v233
	s_nop 1
	v_cndmask_b32_e32 v223, v221, v215, vcc
	v_div_scale_f32 v224, s[0:1], v223, v223, 1.0
	v_rcp_f32_e32 v225, v224
	v_div_scale_f32 v226, vcc, 1.0, v223, 1.0
	v_fma_f32 v227, -v224, v225, 1.0
	v_fmac_f32_e32 v225, v227, v225
	v_mul_f32_e32 v228, v226, v225
	v_fma_f32 v229, -v224, v228, v226
	v_fmac_f32_e32 v228, v229, v225
	v_fma_f32 v227, -v224, v228, v226
	v_div_fmas_f32 v230, v227, v225, v228
	v_div_fixup_f32 v231, v230, v223, 1.0
	s_nop 1
	v_readlane_b32 s52, v231, 7
	s_nop 1
	s_waitcnt vmcnt(58)
; __device__ __forceinline__ void phase_final(const Params& p) {
;     ...
;             const f32x4* sp = (const f32x4*)(ssq + (size_t)row * 32); f32x4 s = sp[0];
; #pragma unroll
;             for (int i = 1; i < 8; ++i) s += sp[i];
;             rs[u] = 1.0f / sqrtf(((s[0] + s[1]) + (s[2] + s[3])) * (1.0f / DM) + 1e-6f); }
; #pragma unroll
;         for (int u = 0; u < UR; ++u) { f32x4* xr = (f32x4*)(p.out + (size_t)(row0 + u * NGW) * DM) + lane;
; #pragma unroll
;             for (int j = 0; j < 8; ++j) __builtin_nontemporal_store(v[u][j] * rs[u] * g4[j], xr + 64 * j); } }
	v_pk_mul_f32 v[196:197], v[32:33], s[52:53] op_sel_hi:[1,0]
	v_pk_mul_f32 v[198:199], v[34:35], s[52:53] op_sel_hi:[1,0]
	v_pk_mul_f32 v[196:197], v[0:1], v[196:197]
	v_pk_mul_f32 v[198:199], v[2:3], v[198:199]
	global_store_dwordx4 v241, v[196:199], s[44:45] nt
	s_waitcnt vmcnt(58)
	v_pk_mul_f32 v[200:201], v[36:37], s[52:53] op_sel_hi:[1,0]
	v_pk_mul_f32 v[202:203], v[38:39], s[52:53] op_sel_hi:[1,0]
	v_pk_mul_f32 v[200:201], v[4:5], v[200:201]
	v_pk_mul_f32 v[202:203], v[6:7], v[202:203]
	global_store_dwordx4 v241, v[200:203], s[44:45] offset:1024 nt
	s_waitcnt vmcnt(58)
	v_pk_mul_f32 v[204:205], v[40:41], s[52:53] op_sel_hi:[1,0]
	v_pk_mul_f32 v[206:207], v[42:43], s[52:53] op_sel_hi:[1,0]
	v_pk_mul_f32 v[204:205], v[8:9], v[204:205]
	v_pk_mul_f32 v[206:207], v[10:11], v[206:207]
	global_store_dwordx4 v241, v[204:207], s[44:45] offset:2048 nt
	s_waitcnt vmcnt(58)
	v_pk_mul_f32 v[208:209], v[44:45], s[52:53] op_sel_hi:[1,0]
	v_pk_mul_f32 v[210:211], v[46:47], s[52:53] op_sel_hi:[1,0]
	v_pk_mul_f32 v[208:209], v[12:13], v[208:209]
	v_pk_mul_f32 v[210:211], v[14:15], v[210:211]
	global_store_dwordx4 v241, v[208:211], s[44:45] offset:3072 nt
	s_waitcnt vmcnt(58)
	v_pk_mul_f32 v[196:197], v[48:49], s[52:53] op_sel_hi:[1,0]
	v_pk_mul_f32 v[198:199], v[50:51], s[52:53] op_sel_hi:[1,0]
	v_pk_mul_f32 v[196:197], v[16:17], v[196:197]
	v_pk_mul_f32 v[198:199], v[18:19], v[198:199]
	global_store_dwordx4 v242, v[196:199], s[44:45] nt
	s_waitcnt vmcnt(58)
	v_pk_mul_f32 v[200:201], v[52:53], s[52:53] op_sel_hi:[1,0]
	v_pk_mul_f32 v[202:203], v[54:55], s[52:53] op_sel_hi:[1,0]
	v_pk_mul_f32 v[200:201], v[20:21], v[200:201]
	v_pk_mul_f32 v[202:203], v[22:23], v[202:203]
	global_store_dwordx4 v242, v[200:203], s[44:45] offset:1024 nt
	s_waitcnt vmcnt(58)
	v_pk_mul_f32 v[204:205], v[56:57], s[52:53] op_sel_hi:[1,0]
	v_pk_mul_f32 v[206:207], v[58:59], s[52:53] op_sel_hi:[1,0]
	v_pk_mul_f32 v[204:205], v[24:25], v[204:205]
	v_pk_mul_f32 v[206:207], v[26:27], v[206:207]
	global_store_dwordx4 v242, v[204:207], s[44:45] offset:2048 nt
	s_waitcnt vmcnt(58)
	v_pk_mul_f32 v[208:209], v[60:61], s[52:53] op_sel_hi:[1,0]
	v_pk_mul_f32 v[210:211], v[62:63], s[52:53] op_sel_hi:[1,0]
	v_pk_mul_f32 v[208:209], v[28:29], v[208:209]
	v_pk_mul_f32 v[210:211], v[30:31], v[210:211]
	global_store_dwordx4 v242, v[208:211], s[44:45] offset:3072 nt
	s_waitcnt vmcnt(50)
	v_mov_b32_e32 v180, v164
	v_mov_b32_e32 v181, v165
	v_mov_b32_e32 v182, v166
	v_mov_b32_e32 v183, v167
	v_add_f32_dpp v180, v180, v164 row_shr:1 row_mask:0xf bank_mask:0xf
	v_add_f32_dpp v181, v181, v165 row_shr:1 row_mask:0xf bank_mask:0xf
	v_add_f32_dpp v182, v182, v166 row_shr:1 row_mask:0xf bank_mask:0xf
	v_add_f32_dpp v183, v183, v167 row_shr:1 row_mask:0xf bank_mask:0xf
	v_add_f32_dpp v180, v180, v164 row_shr:1 row_mask:0xf bank_mask:0xf
	v_add_f32_dpp v181, v181, v165 row_shr:1 row_mask:0xf bank_mask:0xf
	v_add_f32_dpp v182, v182, v166 row_shr:1 row_mask:0xf bank_mask:0xf
	v_add_f32_dpp v183, v183, v167 row_shr:1 row_mask:0xf bank_mask:0xf
	v_add_f32_dpp v180, v180, v164 row_shr:1 row_mask:0xf bank_mask:0xf
	v_add_f32_dpp v181, v181, v165 row_shr:1 row_mask:0xf bank_mask:0xf
	v_add_f32_dpp v182, v182, v166 row_shr:1 row_mask:0xf bank_mask:0xf
	v_add_f32_dpp v183, v183, v167 row_shr:1 row_mask:0xf bank_mask:0xf
	v_add_f32_dpp v180, v180, v164 row_shr:1 row_mask:0xf bank_mask:0xf
	v_add_f32_dpp v181, v181, v165 row_shr:1 row_mask:0xf bank_mask:0xf
	v_add_f32_dpp v182, v182, v166 row_shr:1 row_mask:0xf bank_mask:0xf
	v_add_f32_dpp v183, v183, v167 row_shr:1 row_mask:0xf bank_mask:0xf
	v_add_f32_dpp v180, v180, v164 row_shr:1 row_mask:0xf bank_mask:0xf
	v_add_f32_dpp v181, v181, v165 row_shr:1 row_mask:0xf bank_mask:0xf
	v_add_f32_dpp v182, v182, v166 row_shr:1 row_mask:0xf bank_mask:0xf
	v_add_f32_dpp v183, v183, v167 row_shr:1 row_mask:0xf bank_mask:0xf
	v_add_f32_dpp v180, v180, v164 row_shr:1 row_mask:0xf bank_mask:0xf
	v_add_f32_dpp v181, v181, v165 row_shr:1 row_mask:0xf bank_mask:0xf
	v_add_f32_dpp v182, v182, v166 row_shr:1 row_mask:0xf bank_mask:0xf
	v_add_f32_dpp v183, v183, v167 row_shr:1 row_mask:0xf bank_mask:0xf
	v_add_f32_dpp v180, v180, v164 row_shr:1 row_mask:0xf bank_mask:0xf
	v_add_f32_dpp v181, v181, v165 row_shr:1 row_mask:0xf bank_mask:0xf
	v_add_f32_dpp v182, v182, v166 row_shr:1 row_mask:0xf bank_mask:0xf
	v_add_f32_dpp v183, v183, v167 row_shr:1 row_mask:0xf bank_mask:0xf
	v_add_f32_e32 v227, v181, v180
	v_add_f32_e32 v229, v182, v183
	v_add_f32_e32 v212, v227, v229
	v_fmamk_f32 v213, v212, 0x3a000000, v232
	v_mul_f32_e32 v214, 0x4f800000, v213
	v_cmp_gt_f32_e32 vcc, s10, v213
	s_nop 1
	v_cndmask_b32_e32 v215, v213, v214, vcc
	v_sqrt_f32_e32 v216, v215
	s_nop 0
	v_add_u32_e32 v217, -1, v216
	v_add_u32_e32 v218, 1, v216
	v_fma_f32 v219, -v217, v216, v215
	v_fma_f32 v220, -v218, v216, v215
	v_cmp_ge_f32_e64 s[0:1], 0, v219
	s_nop 1
	v_cndmask_b32_e64 v221, v216, v217, s[0:1]
	v_cmp_lt_f32_e64 s[0:1], 0, v220
	s_nop 1
	v_cndmask_b32_e64 v221, v221, v218, s[0:1]
	v_mul_f32_e32 v222, 0x37800000, v221
	v_cndmask_b32_e32 v221, v221, v222, vcc
	v_cmp_class_f32_e32 vcc, v215, v233
	s_nop 1
	v_cndmask_b32_e32 v223, v221, v215, vcc
	v_div_scale_f32 v224, s[0:1], v223, v223, 1.0
	v_rcp_f32_e32 v225, v224
	v_div_scale_f32 v226, vcc, 1.0, v223, 1.0
	v_fma_f32 v227, -v224, v225, 1.0
	v_fmac_f32_e32 v225, v227, v225
	v_mul_f32_e32 v228, v226, v225
	v_fma_f32 v229, -v224, v228, v226
	v_fmac_f32_e32 v228, v229, v225
	v_fma_f32 v227, -v224, v228, v226
	v_div_fmas_f32 v230, v227, v225, v228
	v_div_fixup_f32 v231, v230, v223, 1.0
	s_nop 1
	v_readlane_b32 s54, v231, 7
	s_nop 1
	s_waitcnt vmcnt(49)
; __device__ __forceinline__ void phase_final(const Params& p) {
;     ...
;             const f32x4* sp = (const f32x4*)(ssq + (size_t)row * 32); f32x4 s = sp[0];
; #pragma unroll
;             for (int i = 1; i < 8; ++i) s += sp[i];
;             rs[u] = 1.0f / sqrtf(((s[0] + s[1]) + (s[2] + s[3])) * (1.0f / DM) + 1e-6f); }
; #pragma unroll
;         for (int u = 0; u < UR; ++u) { f32x4* xr = (f32x4*)(p.out + (size_t)(row0 + u * NGW) * DM) + lane;
; #pragma unroll
;             for (int j = 0; j < 8; ++j) __builtin_nontemporal_store(v[u][j] * rs[u] * g4[j], xr + 64 * j); } }
	v_pk_mul_f32 v[196:197], v[64:65], s[54:55] op_sel_hi:[1,0]
	v_pk_mul_f32 v[198:199], v[66:67], s[54:55] op_sel_hi:[1,0]
	v_pk_mul_f32 v[196:197], v[0:1], v[196:197]
	v_pk_mul_f32 v[198:199], v[2:3], v[198:199]
	global_store_dwordx4 v241, v[196:199], s[46:47] nt
	s_waitcnt vmcnt(49)
	v_pk_mul_f32 v[200:201], v[68:69], s[54:55] op_sel_hi:[1,0]
	v_pk_mul_f32 v[202:203], v[70:71], s[54:55] op_sel_hi:[1,0]
	v_pk_mul_f32 v[200:201], v[4:5], v[200:201]
	v_pk_mul_f32 v[202:203], v[6:7], v[202:203]
	global_store_dwordx4 v241, v[200:203], s[46:47] offset:1024 nt
	s_waitcnt vmcnt(49)
	v_pk_mul_f32 v[204:205], v[72:73], s[54:55] op_sel_hi:[1,0]
	v_pk_mul_f32 v[206:207], v[74:75], s[54:55] op_sel_hi:[1,0]
	v_pk_mul_f32 v[204:205], v[8:9], v[204:205]
	v_pk_mul_f32 v[206:207], v[10:11], v[206:207]
	global_store_dwordx4 v241, v[204:207], s[46:47] offset:2048 nt
	s_waitcnt vmcnt(49)
	v_pk_mul_f32 v[208:209], v[76:77], s[54:55] op_sel_hi:[1,0]
	v_pk_mul_f32 v[210:211], v[78:79], s[54:55] op_sel_hi:[1,0]
	v_pk_mul_f32 v[208:209], v[12:13], v[208:209]
	v_pk_mul_f32 v[210:211], v[14:15], v[210:211]
	global_store_dwordx4 v241, v[208:211], s[46:47] offset:3072 nt
	s_waitcnt vmcnt(49)
	v_pk_mul_f32 v[196:197], v[80:81], s[54:55] op_sel_hi:[1,0]
	v_pk_mul_f32 v[198:199], v[82:83], s[54:55] op_sel_hi:[1,0]
	v_pk_mul_f32 v[196:197], v[16:17], v[196:197]
	v_pk_mul_f32 v[198:199], v[18:19], v[198:199]
	global_store_dwordx4 v242, v[196:199], s[46:47] nt
	s_waitcnt vmcnt(49)
	v_pk_mul_f32 v[200:201], v[84:85], s[54:55] op_sel_hi:[1,0]
	v_pk_mul_f32 v[202:203], v[86:87], s[54:55] op_sel_hi:[1,0]
	v_pk_mul_f32 v[200:201], v[20:21], v[200:201]
	v_pk_mul_f32 v[202:203], v[22:23], v[202:203]
	global_store_dwordx4 v242, v[200:203], s[46:47] offset:1024 nt
	s_waitcnt vmcnt(49)
	v_pk_mul_f32 v[204:205], v[88:89], s[54:55] op_sel_hi:[1,0]
	v_pk_mul_f32 v[206:207], v[90:91], s[54:55] op_sel_hi:[1,0]
	v_pk_mul_f32 v[204:205], v[24:25], v[204:205]
	v_pk_mul_f32 v[206:207], v[26:27], v[206:207]
	global_store_dwordx4 v242, v[204:207], s[46:47] offset:2048 nt
	s_waitcnt vmcnt(49)
	v_pk_mul_f32 v[208:209], v[92:93], s[54:55] op_sel_hi:[1,0]
	v_pk_mul_f32 v[210:211], v[94:95], s[54:55] op_sel_hi:[1,0]
	v_pk_mul_f32 v[208:209], v[28:29], v[208:209]
	v_pk_mul_f32 v[210:211], v[30:31], v[210:211]
	global_store_dwordx4 v242, v[208:211], s[46:47] offset:3072 nt
	s_waitcnt vmcnt(41)
	v_mov_b32_e32 v184, v168
	v_mov_b32_e32 v185, v169
	v_mov_b32_e32 v186, v170
	v_mov_b32_e32 v187, v171
	v_add_f32_dpp v184, v184, v168 row_shr:1 row_mask:0xf bank_mask:0xf
	v_add_f32_dpp v185, v185, v169 row_shr:1 row_mask:0xf bank_mask:0xf
	v_add_f32_dpp v186, v186, v170 row_shr:1 row_mask:0xf bank_mask:0xf
	v_add_f32_dpp v187, v187, v171 row_shr:1 row_mask:0xf bank_mask:0xf
	v_add_f32_dpp v184, v184, v168 row_shr:1 row_mask:0xf bank_mask:0xf
	v_add_f32_dpp v185, v185, v169 row_shr:1 row_mask:0xf bank_mask:0xf
	v_add_f32_dpp v186, v186, v170 row_shr:1 row_mask:0xf bank_mask:0xf
	v_add_f32_dpp v187, v187, v171 row_shr:1 row_mask:0xf bank_mask:0xf
	v_add_f32_dpp v184, v184, v168 row_shr:1 row_mask:0xf bank_mask:0xf
	v_add_f32_dpp v185, v185, v169 row_shr:1 row_mask:0xf bank_mask:0xf
	v_add_f32_dpp v186, v186, v170 row_shr:1 row_mask:0xf bank_mask:0xf
	v_add_f32_dpp v187, v187, v171 row_shr:1 row_mask:0xf bank_mask:0xf
	v_add_f32_dpp v184, v184, v168 row_shr:1 row_mask:0xf bank_mask:0xf
	v_add_f32_dpp v185, v185, v169 row_shr:1 row_mask:0xf bank_mask:0xf
	v_add_f32_dpp v186, v186, v170 row_shr:1 row_mask:0xf bank_mask:0xf
	v_add_f32_dpp v187, v187, v171 row_shr:1 row_mask:0xf bank_mask:0xf
	v_add_f32_dpp v184, v184, v168 row_shr:1 row_mask:0xf bank_mask:0xf
	v_add_f32_dpp v185, v185, v169 row_shr:1 row_mask:0xf bank_mask:0xf
	v_add_f32_dpp v186, v186, v170 row_shr:1 row_mask:0xf bank_mask:0xf
	v_add_f32_dpp v187, v187, v171 row_shr:1 row_mask:0xf bank_mask:0xf
	v_add_f32_dpp v184, v184, v168 row_shr:1 row_mask:0xf bank_mask:0xf
	v_add_f32_dpp v185, v185, v169 row_shr:1 row_mask:0xf bank_mask:0xf
	v_add_f32_dpp v186, v186, v170 row_shr:1 row_mask:0xf bank_mask:0xf
	v_add_f32_dpp v187, v187, v171 row_shr:1 row_mask:0xf bank_mask:0xf
	v_add_f32_dpp v184, v184, v168 row_shr:1 row_mask:0xf bank_mask:0xf
	v_add_f32_dpp v185, v185, v169 row_shr:1 row_mask:0xf bank_mask:0xf
	v_add_f32_dpp v186, v186, v170 row_shr:1 row_mask:0xf bank_mask:0xf
	v_add_f32_dpp v187, v187, v171 row_shr:1 row_mask:0xf bank_mask:0xf
	v_add_f32_e32 v227, v185, v184
	v_add_f32_e32 v229, v186, v187
	v_add_f32_e32 v212, v227, v229
	v_fmamk_f32 v213, v212, 0x3a000000, v232
	v_mul_f32_e32 v214, 0x4f800000, v213
	v_cmp_gt_f32_e32 vcc, s10, v213
	s_nop 1
	v_cndmask_b32_e32 v215, v213, v214, vcc
	v_sqrt_f32_e32 v216, v215
	s_nop 0
	v_add_u32_e32 v217, -1, v216
	v_add_u32_e32 v218, 1, v216
	v_fma_f32 v219, -v217, v216, v215
	v_fma_f32 v220, -v218, v216, v215
	v_cmp_ge_f32_e64 s[0:1], 0, v219
	s_nop 1
	v_cndmask_b32_e64 v221, v216, v217, s[0:1]
	v_cmp_lt_f32_e64 s[0:1], 0, v220
	s_nop 1
	v_cndmask_b32_e64 v221, v221, v218, s[0:1]
	v_mul_f32_e32 v222, 0x37800000, v221
	v_cndmask_b32_e32 v221, v221, v222, vcc
	v_cmp_class_f32_e32 vcc, v215, v233
	s_nop 1
	v_cndmask_b32_e32 v223, v221, v215, vcc
	v_div_scale_f32 v224, s[0:1], v223, v223, 1.0
	v_rcp_f32_e32 v225, v224
	v_div_scale_f32 v226, vcc, 1.0, v223, 1.0
	v_fma_f32 v227, -v224, v225, 1.0
	v_fmac_f32_e32 v225, v227, v225
	v_mul_f32_e32 v228, v226, v225
	v_fma_f32 v229, -v224, v228, v226
	v_fmac_f32_e32 v228, v229, v225
	v_fma_f32 v227, -v224, v228, v226
	v_div_fmas_f32 v230, v227, v225, v228
	v_div_fixup_f32 v231, v230, v223, 1.0
	s_nop 1
	v_readlane_b32 s56, v231, 7
	s_nop 1
	s_waitcnt vmcnt(40)
; __device__ __forceinline__ void phase_final(const Params& p) {
;     ...
;         for (int u = 0; u < UR; ++u) { const int row = row0 + u * NGW; const f32x4* xr = (const f32x4*)(p.out + (size_t)row * DM) + lane;
; #pragma unroll
;             for (int j = 0; j < 8; ++j) v[u][j] = xr[64 * j];
;             const f32x4* sp = (const f32x4*)(ssq + (size_t)row * 32); f32x4 s = sp[0];
; #pragma unroll
;             for (int i = 1; i < 8; ++i) s += sp[i];
;             rs[u] = 1.0f / sqrtf(((s[0] + s[1]) + (s[2] + s[3])) * (1.0f / DM) + 1e-6f); }
; #pragma unroll
;         for (int u = 0; u < UR; ++u) { f32x4* xr = (f32x4*)(p.out + (size_t)(row0 + u * NGW) * DM) + lane;
; #pragma unroll
;             for (int j = 0; j < 8; ++j) __builtin_nontemporal_store(v[u][j] * rs[u] * g4[j], xr + 64 * j); } }
	v_pk_mul_f32 v[196:197], v[96:97], s[56:57] op_sel_hi:[1,0]
	v_pk_mul_f32 v[198:199], v[98:99], s[56:57] op_sel_hi:[1,0]
	v_pk_mul_f32 v[196:197], v[0:1], v[196:197]
	v_pk_mul_f32 v[198:199], v[2:3], v[198:199]
	global_store_dwordx4 v241, v[196:199], s[48:49] nt
	s_waitcnt vmcnt(40)
	v_pk_mul_f32 v[200:201], v[100:101], s[56:57] op_sel_hi:[1,0]
	v_pk_mul_f32 v[202:203], v[102:103], s[56:57] op_sel_hi:[1,0]
	v_pk_mul_f32 v[200:201], v[4:5], v[200:201]
	v_pk_mul_f32 v[202:203], v[6:7], v[202:203]
	global_store_dwordx4 v241, v[200:203], s[48:49] offset:1024 nt
	s_waitcnt vmcnt(40)
	v_pk_mul_f32 v[204:205], v[104:105], s[56:57] op_sel_hi:[1,0]
	v_pk_mul_f32 v[206:207], v[106:107], s[56:57] op_sel_hi:[1,0]
	v_pk_mul_f32 v[204:205], v[8:9], v[204:205]
	v_pk_mul_f32 v[206:207], v[10:11], v[206:207]
	global_store_dwordx4 v241, v[204:207], s[48:49] offset:2048 nt
	s_waitcnt vmcnt(40)
	v_pk_mul_f32 v[208:209], v[108:109], s[56:57] op_sel_hi:[1,0]
	v_pk_mul_f32 v[210:211], v[110:111], s[56:57] op_sel_hi:[1,0]
	v_pk_mul_f32 v[208:209], v[12:13], v[208:209]
	v_pk_mul_f32 v[210:211], v[14:15], v[210:211]
	global_store_dwordx4 v241, v[208:211], s[48:49] offset:3072 nt
	s_waitcnt vmcnt(40)
	v_pk_mul_f32 v[196:197], v[112:113], s[56:57] op_sel_hi:[1,0]
	v_pk_mul_f32 v[198:199], v[114:115], s[56:57] op_sel_hi:[1,0]
	v_pk_mul_f32 v[196:197], v[16:17], v[196:197]
	v_pk_mul_f32 v[198:199], v[18:19], v[198:199]
	global_store_dwordx4 v242, v[196:199], s[48:49] nt
	s_waitcnt vmcnt(40)
	v_pk_mul_f32 v[200:201], v[116:117], s[56:57] op_sel_hi:[1,0]
	v_pk_mul_f32 v[202:203], v[118:119], s[56:57] op_sel_hi:[1,0]
	v_pk_mul_f32 v[200:201], v[20:21], v[200:201]
	v_pk_mul_f32 v[202:203], v[22:23], v[202:203]
	global_store_dwordx4 v242, v[200:203], s[48:49] offset:1024 nt
	s_waitcnt vmcnt(40)
	v_pk_mul_f32 v[204:205], v[120:121], s[56:57] op_sel_hi:[1,0]
	v_pk_mul_f32 v[206:207], v[122:123], s[56:57] op_sel_hi:[1,0]
	v_pk_mul_f32 v[204:205], v[24:25], v[204:205]
	v_pk_mul_f32 v[206:207], v[26:27], v[206:207]
	global_store_dwordx4 v242, v[204:207], s[48:49] offset:2048 nt
	s_waitcnt vmcnt(40)
	v_pk_mul_f32 v[208:209], v[124:125], s[56:57] op_sel_hi:[1,0]
	v_pk_mul_f32 v[210:211], v[126:127], s[56:57] op_sel_hi:[1,0]
	v_pk_mul_f32 v[208:209], v[28:29], v[208:209]
	v_pk_mul_f32 v[210:211], v[30:31], v[210:211]
	global_store_dwordx4 v242, v[208:211], s[48:49] offset:3072 nt
	s_waitcnt vmcnt(32)
; __device__ __forceinline__ void phase_final(const Params& p) {
;     ...
;             const f32x4* sp = (const f32x4*)(ssq + (size_t)row * 32); f32x4 s = sp[0];
; #pragma unroll
;             for (int i = 1; i < 8; ++i) s += sp[i];
;             rs[u] = 1.0f / sqrtf(((s[0] + s[1]) + (s[2] + s[3])) * (1.0f / DM) + 1e-6f); }
; #pragma unroll
;         for (int u = 0; u < UR; ++u) { f32x4* xr = (f32x4*)(p.out + (size_t)(row0 + u * NGW) * DM) + lane;
; #pragma unroll
;             for (int j = 0; j < 8; ++j) __builtin_nontemporal_store(v[u][j] * rs[u] * g4[j], xr + 64 * j); } }
	v_mov_b32_e32 v188, v172
	v_mov_b32_e32 v189, v173
	v_mov_b32_e32 v190, v174
	v_mov_b32_e32 v191, v175
	v_add_f32_dpp v188, v188, v172 row_shr:1 row_mask:0xf bank_mask:0xf
	v_add_f32_dpp v189, v189, v173 row_shr:1 row_mask:0xf bank_mask:0xf
	v_add_f32_dpp v190, v190, v174 row_shr:1 row_mask:0xf bank_mask:0xf
	v_add_f32_dpp v191, v191, v175 row_shr:1 row_mask:0xf bank_mask:0xf
	v_add_f32_dpp v188, v188, v172 row_shr:1 row_mask:0xf bank_mask:0xf
	v_add_f32_dpp v189, v189, v173 row_shr:1 row_mask:0xf bank_mask:0xf
	v_add_f32_dpp v190, v190, v174 row_shr:1 row_mask:0xf bank_mask:0xf
	v_add_f32_dpp v191, v191, v175 row_shr:1 row_mask:0xf bank_mask:0xf
	v_add_f32_dpp v188, v188, v172 row_shr:1 row_mask:0xf bank_mask:0xf
	v_add_f32_dpp v189, v189, v173 row_shr:1 row_mask:0xf bank_mask:0xf
	v_add_f32_dpp v190, v190, v174 row_shr:1 row_mask:0xf bank_mask:0xf
	v_add_f32_dpp v191, v191, v175 row_shr:1 row_mask:0xf bank_mask:0xf
	v_add_f32_dpp v188, v188, v172 row_shr:1 row_mask:0xf bank_mask:0xf
	v_add_f32_dpp v189, v189, v173 row_shr:1 row_mask:0xf bank_mask:0xf
	v_add_f32_dpp v190, v190, v174 row_shr:1 row_mask:0xf bank_mask:0xf
	v_add_f32_dpp v191, v191, v175 row_shr:1 row_mask:0xf bank_mask:0xf
	v_add_f32_dpp v188, v188, v172 row_shr:1 row_mask:0xf bank_mask:0xf
	v_add_f32_dpp v189, v189, v173 row_shr:1 row_mask:0xf bank_mask:0xf
	v_add_f32_dpp v190, v190, v174 row_shr:1 row_mask:0xf bank_mask:0xf
	v_add_f32_dpp v191, v191, v175 row_shr:1 row_mask:0xf bank_mask:0xf
	v_add_f32_dpp v188, v188, v172 row_shr:1 row_mask:0xf bank_mask:0xf
	v_add_f32_dpp v189, v189, v173 row_shr:1 row_mask:0xf bank_mask:0xf
	v_add_f32_dpp v190, v190, v174 row_shr:1 row_mask:0xf bank_mask:0xf
	v_add_f32_dpp v191, v191, v175 row_shr:1 row_mask:0xf bank_mask:0xf
	v_add_f32_dpp v188, v188, v172 row_shr:1 row_mask:0xf bank_mask:0xf
	v_add_f32_dpp v189, v189, v173 row_shr:1 row_mask:0xf bank_mask:0xf
	v_add_f32_dpp v190, v190, v174 row_shr:1 row_mask:0xf bank_mask:0xf
	v_add_f32_dpp v191, v191, v175 row_shr:1 row_mask:0xf bank_mask:0xf
	v_add_f32_e32 v227, v189, v188
	v_add_f32_e32 v229, v190, v191
	v_add_f32_e32 v212, v227, v229
	v_fmamk_f32 v213, v212, 0x3a000000, v232
	v_mul_f32_e32 v214, 0x4f800000, v213
	v_cmp_gt_f32_e32 vcc, s10, v213
	s_nop 1
	v_cndmask_b32_e32 v215, v213, v214, vcc
	v_sqrt_f32_e32 v216, v215
	s_nop 0
	v_add_u32_e32 v217, -1, v216
	v_add_u32_e32 v218, 1, v216
	v_fma_f32 v219, -v217, v216, v215
	v_fma_f32 v220, -v218, v216, v215
	v_cmp_ge_f32_e64 s[0:1], 0, v219
	s_nop 1
	v_cndmask_b32_e64 v221, v216, v217, s[0:1]
	v_cmp_lt_f32_e64 s[0:1], 0, v220
	s_nop 1
	v_cndmask_b32_e64 v221, v221, v218, s[0:1]
	v_mul_f32_e32 v222, 0x37800000, v221
	v_cndmask_b32_e32 v221, v221, v222, vcc
	v_cmp_class_f32_e32 vcc, v215, v233
	s_nop 1
	v_cndmask_b32_e32 v223, v221, v215, vcc
	v_div_scale_f32 v224, s[0:1], v223, v223, 1.0
	v_rcp_f32_e32 v225, v224
	v_div_scale_f32 v226, vcc, 1.0, v223, 1.0
	v_fma_f32 v227, -v224, v225, 1.0
	v_fmac_f32_e32 v225, v227, v225
	v_mul_f32_e32 v228, v226, v225
	v_fma_f32 v229, -v224, v228, v226
	v_fmac_f32_e32 v228, v229, v225
	v_fma_f32 v227, -v224, v228, v226
	v_div_fmas_f32 v230, v227, v225, v228
	v_div_fixup_f32 v231, v230, v223, 1.0
	s_nop 1
	v_readlane_b32 s58, v231, 7
	s_nop 1
	s_waitcnt vmcnt(31)
	v_pk_mul_f32 v[196:197], v[128:129], s[58:59] op_sel_hi:[1,0]
	v_pk_mul_f32 v[198:199], v[130:131], s[58:59] op_sel_hi:[1,0]
	v_pk_mul_f32 v[196:197], v[0:1], v[196:197]
	v_pk_mul_f32 v[198:199], v[2:3], v[198:199]
	global_store_dwordx4 v241, v[196:199], s[50:51] nt
	s_waitcnt vmcnt(31)
	v_pk_mul_f32 v[200:201], v[132:133], s[58:59] op_sel_hi:[1,0]
	v_pk_mul_f32 v[202:203], v[134:135], s[58:59] op_sel_hi:[1,0]
	v_pk_mul_f32 v[200:201], v[4:5], v[200:201]
	v_pk_mul_f32 v[202:203], v[6:7], v[202:203]
	global_store_dwordx4 v241, v[200:203], s[50:51] offset:1024 nt
	s_waitcnt vmcnt(31)
	v_pk_mul_f32 v[204:205], v[136:137], s[58:59] op_sel_hi:[1,0]
	v_pk_mul_f32 v[206:207], v[138:139], s[58:59] op_sel_hi:[1,0]
	v_pk_mul_f32 v[204:205], v[8:9], v[204:205]
	v_pk_mul_f32 v[206:207], v[10:11], v[206:207]
	global_store_dwordx4 v241, v[204:207], s[50:51] offset:2048 nt
	s_waitcnt vmcnt(31)
	v_pk_mul_f32 v[208:209], v[140:141], s[58:59] op_sel_hi:[1,0]
	v_pk_mul_f32 v[210:211], v[142:143], s[58:59] op_sel_hi:[1,0]
	v_pk_mul_f32 v[208:209], v[12:13], v[208:209]
	v_pk_mul_f32 v[210:211], v[14:15], v[210:211]
	global_store_dwordx4 v241, v[208:211], s[50:51] offset:3072 nt
	s_waitcnt vmcnt(31)
	v_pk_mul_f32 v[196:197], v[144:145], s[58:59] op_sel_hi:[1,0]
	v_pk_mul_f32 v[198:199], v[146:147], s[58:59] op_sel_hi:[1,0]
	v_pk_mul_f32 v[196:197], v[16:17], v[196:197]
	v_pk_mul_f32 v[198:199], v[18:19], v[198:199]
	global_store_dwordx4 v242, v[196:199], s[50:51] nt
	s_waitcnt vmcnt(31)
	v_pk_mul_f32 v[200:201], v[148:149], s[58:59] op_sel_hi:[1,0]
	v_pk_mul_f32 v[202:203], v[150:151], s[58:59] op_sel_hi:[1,0]
	v_pk_mul_f32 v[200:201], v[20:21], v[200:201]
	v_pk_mul_f32 v[202:203], v[22:23], v[202:203]
	global_store_dwordx4 v242, v[200:203], s[50:51] offset:1024 nt
	s_waitcnt vmcnt(31)
	v_pk_mul_f32 v[204:205], v[152:153], s[58:59] op_sel_hi:[1,0]
	v_pk_mul_f32 v[206:207], v[154:155], s[58:59] op_sel_hi:[1,0]
	v_pk_mul_f32 v[204:205], v[24:25], v[204:205]
	v_pk_mul_f32 v[206:207], v[26:27], v[206:207]
	global_store_dwordx4 v242, v[204:207], s[50:51] offset:2048 nt
	s_waitcnt vmcnt(31)
	v_pk_mul_f32 v[208:209], v[156:157], s[58:59] op_sel_hi:[1,0]
	v_pk_mul_f32 v[210:211], v[158:159], s[58:59] op_sel_hi:[1,0]
	v_pk_mul_f32 v[208:209], v[28:29], v[208:209]
	v_pk_mul_f32 v[210:211], v[30:31], v[210:211]
	global_store_dwordx4 v242, v[208:211], s[50:51] offset:3072 nt
